# speedup vs baseline: 1.0136x; 1.0026x over previous
; __device__ __forceinline__ f16v mfma16(h8 a, h8 b, f16v c) { return __builtin_amdgcn_mfma_f32_32x32x16_f16(a, b, c, 0, 0, 0); }
; template <int EQK, int EV, bool PF, class KP, class SC>
; __device__ __forceinline__ void flash_core(f16v (&o)[EV / 32], float& m_run, float& l_run, const h8 (&qf)[EQK / 16],
;                                            int kt0, int kt1, const KP& kp, const SC& sc, char* smem) {
;     ...
;       h8 pf[4];
; #pragma unroll
;       for (int i = 0; i < 8; ++i) { pf[0][i] = (h16)p0[i]; pf[1][i] = (h16)p0[8 + i]; pf[2][i] = (h16)p1[i]; pf[3][i] = (h16)p1[8 + i]; }
; #pragma unroll
;       for (int et = 0; et < EV / 32; ++et) {
;         const h16* vb = sV + (et * 32 + l31) * VLD + hi * 4;
; #pragma unroll
;         for (int ks = 0; ks < 4; ++ks) {
;           h4 lo = *(const h4*)(vb + ks * 16), hh = *(const h4*)(vb + ks * 16 + 8);
;           h8 vf = {lo[0], lo[1], lo[2], lo[3], hh[0], hh[1], hh[2], hh[3]};
;           o[et] = mfma16(vf, pf[ks], o[et]);
;         }
;       }
; __device__ __forceinline__ void diff_attn_phase(const P& p_, int j, float lam_init, char* smem, bool dry = false) {
;     ...
;       const float inv = 1.f / l_run;
;       if (c == 0) {
; #pragma unroll
;         for (int et = 0; et < 4; ++et)
; #pragma unroll
;           for (int rg = 0; rg < 2; ++rg) {
;             h8 sv;
; #pragma unroll
;             for (int i = 0; i < 8; ++i) sv[i] = (h16)(o[et][rg * 8 + i] * inv);
;             *(h8*)(stash + et * 16 + rg * 8) = sv;
;           }
;       } else {
; #pragma unroll
;         for (int et = 0; et < 4; ++et)
; #pragma unroll
;           for (int rg = 0; rg < 2; ++rg) {
;             const h8 sv = *(const h8*)(stash + et * 16 + rg * 8);
; #pragma unroll
;             for (int i = 0; i < 8; ++i) o[et][rg * 8 + i] = (float)sv[i] - lam_full * (o[et][rg * 8 + i] * inv);
.LBB0_1094:
	v_add_f32_e32 v112, v99, v100
	v_fmac_f32_e32 v112, v14, v0
	v_lshl_add_u32 v0, v166, 1, s15
	v_add_u32_e32 v0, v253, v0
	v_lshl_add_u32 v14, v145, 1, v0
	v_add_u32_e32 v14, 0x2000, v14
	ds_read_b128 v[100:103], v14 offset:1024
	ds_read_b128 v[104:107], v14 offset:1056
	v_cvt_pk_f16_f32 v111, v83, v85
	v_cvt_pk_f16_f32 v110, v12, v15
	v_cvt_pk_f16_f32 v109, v8, v10
	v_cvt_pk_f16_f32 v108, v4, v6
	v_cvt_pk_f16_f32 v99, v89, v90
	v_cvt_pk_f16_f32 v13, v13, v80
	s_waitcnt lgkmcnt(1)
	v_mfma_f32_32x32x16_f16 v[64:79], v[100:103], v[108:111], v[64:79]
	v_cvt_pk_f16_f32 v101, v97, v98
	v_cvt_pk_f16_f32 v100, v93, v94
	v_cvt_pk_f16_f32 v98, v84, v86
	v_cvt_pk_f16_f32 v12, v9, v11
	v_cvt_pk_f16_f32 v11, v5, v7
	v_cvt_pk_f16_f32 v10, v2, v3
	ds_read_b128 v[2:5], v14 offset:1120
	s_waitcnt lgkmcnt(1)
	v_mfma_f32_32x32x16_f16 v[64:79], v[104:107], v[98:101], v[64:79]
	ds_read_b128 v[102:105], v14 offset:1088
	v_add_u32_e32 v0, v0, v139
	v_cvt_pk_f16_f32 v9, v95, v96
	v_cvt_pk_f16_f32 v8, v91, v92
	v_cvt_pk_f16_f32 v7, v87, v88
	v_cvt_pk_f16_f32 v6, v81, v82
	v_add_u32_e32 v14, 0x3000, v0
	s_waitcnt lgkmcnt(0)
	v_mfma_f32_32x32x16_f16 v[64:79], v[102:105], v[10:13], v[64:79]
	s_lshl_b32 s88, s46, 1
	s_mov_b32 s2, 0x800000
	v_mov_b32_e32 v139, v1
	s_add_i32 s0, s0, s76
	s_add_i32 s27, s27, s75
	s_cmpk_gt_i32 s0, 0x3ff
	v_mfma_f32_32x32x16_f16 v[64:79], v[2:5], v[6:9], v[64:79]
	ds_read_b128 v[2:5], v14 offset:1536
	ds_read_b128 v[80:83], v14 offset:1568
	s_waitcnt lgkmcnt(1)
	v_mfma_f32_32x32x16_f16 v[48:63], v[2:5], v[108:111], v[48:63]
	ds_read_b128 v[2:5], v14 offset:1600
	s_waitcnt lgkmcnt(1)
	v_mfma_f32_32x32x16_f16 v[48:63], v[80:83], v[98:101], v[48:63]
	s_waitcnt lgkmcnt(0)
	v_mfma_f32_32x32x16_f16 v[48:63], v[2:5], v[10:13], v[48:63]
	ds_read_b128 v[2:5], v14 offset:1632
	v_add_u32_e32 v14, 0x4800, v0
	v_add_u32_e32 v0, 0x5800, v0
	s_waitcnt lgkmcnt(0)
	v_mfma_f32_32x32x16_f16 v[48:63], v[2:5], v[6:9], v[48:63]
	ds_read_b128 v[2:5], v14
	s_waitcnt lgkmcnt(0)
	v_mfma_f32_32x32x16_f16 v[32:47], v[2:5], v[108:111], v[32:47]
	ds_read_b128 v[2:5], v14 offset:32
	s_waitcnt lgkmcnt(0)
	v_mfma_f32_32x32x16_f16 v[32:47], v[2:5], v[98:101], v[32:47]
	ds_read_b128 v[2:5], v14 offset:64
	s_waitcnt lgkmcnt(0)
	v_mfma_f32_32x32x16_f16 v[32:47], v[2:5], v[10:13], v[32:47]
	ds_read_b128 v[2:5], v14 offset:96
	s_waitcnt lgkmcnt(0)
	v_mfma_f32_32x32x16_f16 v[32:47], v[2:5], v[6:9], v[32:47]
	ds_read_b128 v[2:5], v0 offset:512
	s_waitcnt lgkmcnt(0)
	v_mfma_f32_32x32x16_f16 v[16:31], v[2:5], v[108:111], v[16:31]
	ds_read_b128 v[2:5], v0 offset:544
	s_waitcnt lgkmcnt(0)
	v_mfma_f32_32x32x16_f16 v[16:31], v[2:5], v[98:101], v[16:31]
	ds_read_b128 v[2:5], v0 offset:576
	s_waitcnt lgkmcnt(0)
	v_mfma_f32_32x32x16_f16 v[16:31], v[2:5], v[10:13], v[16:31]
	ds_read_b128 v[2:5], v0 offset:608
	v_div_scale_f32 v0, s[14:15], v112, v112, 1.0
	s_waitcnt lgkmcnt(0)
	s_barrier
	v_lshlrev_b64 v[10:11], 11, v[140:141]
	v_mfma_f32_32x32x16_f16 v[16:31], v[2:5], v[6:9], v[16:31]
	v_rcp_f32_e32 v2, v0
	v_lshl_add_u64 v[10:11], s[12:13], 0, v[10:11]
	v_lshl_add_u64 v[14:15], v[10:11], 0, s[88:89]
	v_lshl_add_u64 v[14:15], v[14:15], 0, v[138:139]
	v_fma_f32 v3, -v0, v2, 1.0
	v_fmac_f32_e32 v2, v3, v2
	v_div_scale_f32 v3, vcc, 1.0, v112, 1.0
	v_mul_f32_e32 v4, v3, v2
	v_fma_f32 v5, -v0, v4, v3
	v_fmac_f32_e32 v4, v5, v2
	v_fma_f32 v0, -v0, v4, v3
	v_div_fmas_f32 v0, v0, v2, v4
	global_load_dwordx4 v[6:9], v[142:143], off offset:96
	global_load_dwordx4 v[2:5], v[142:143], off offset:112
	global_load_dwordx4 v[84:87], v[142:143], off offset:64
	global_load_dwordx4 v[80:83], v[142:143], off offset:80
	global_load_dwordx4 v[92:95], v[142:143], off offset:32
	global_load_dwordx4 v[88:91], v[142:143], off offset:48
	global_load_dwordx4 v[100:103], v[142:143], off
	global_load_dwordx4 v[96:99], v[142:143], off offset:16
	v_div_fixup_f32 v0, v0, v112, 1.0
	v_pk_mul_f32 v[12:13], v[0:1], v[64:65] op_sel_hi:[0,1]
	v_pk_mul_f32 v[66:67], v[0:1], v[66:67] op_sel_hi:[0,1]
	v_pk_mul_f32 v[68:69], v[0:1], v[68:69] op_sel_hi:[0,1]
	v_pk_mul_f32 v[70:71], v[0:1], v[70:71] op_sel_hi:[0,1]
	v_pk_mul_f32 v[72:73], v[0:1], v[72:73] op_sel_hi:[0,1]
	v_pk_mul_f32 v[74:75], v[0:1], v[74:75] op_sel_hi:[0,1]
	v_pk_mul_f32 v[76:77], v[0:1], v[76:77] op_sel_hi:[0,1]
	v_pk_mul_f32 v[78:79], v[0:1], v[78:79] op_sel_hi:[0,1]
	v_pk_mul_f32 v[48:49], v[0:1], v[48:49] op_sel_hi:[0,1]
	v_pk_mul_f32 v[50:51], v[0:1], v[50:51] op_sel_hi:[0,1]
	v_pk_mul_f32 v[52:53], v[0:1], v[52:53] op_sel_hi:[0,1]
	v_pk_mul_f32 v[54:55], v[0:1], v[54:55] op_sel_hi:[0,1]
	v_pk_mul_f32 v[56:57], v[0:1], v[56:57] op_sel_hi:[0,1]
	v_pk_mul_f32 v[58:59], v[0:1], v[58:59] op_sel_hi:[0,1]
	v_pk_mul_f32 v[60:61], v[0:1], v[60:61] op_sel_hi:[0,1]
	v_pk_mul_f32 v[62:63], v[0:1], v[62:63] op_sel_hi:[0,1]
	v_pk_mul_f32 v[32:33], v[0:1], v[32:33] op_sel_hi:[0,1]
	v_pk_mul_f32 v[34:35], v[0:1], v[34:35] op_sel_hi:[0,1]
	v_pk_mul_f32 v[36:37], v[0:1], v[36:37] op_sel_hi:[0,1]
	v_pk_mul_f32 v[38:39], v[0:1], v[38:39] op_sel_hi:[0,1]
	v_pk_mul_f32 v[40:41], v[0:1], v[40:41] op_sel_hi:[0,1]
	v_pk_mul_f32 v[42:43], v[0:1], v[42:43] op_sel_hi:[0,1]
	v_pk_mul_f32 v[44:45], v[0:1], v[44:45] op_sel_hi:[0,1]
	v_pk_mul_f32 v[46:47], v[0:1], v[46:47] op_sel_hi:[0,1]
	v_pk_mul_f32 v[16:17], v[0:1], v[16:17] op_sel_hi:[0,1]
	v_pk_mul_f32 v[20:21], v[0:1], v[20:21] op_sel_hi:[0,1]
	v_pk_mul_f32 v[24:25], v[0:1], v[24:25] op_sel_hi:[0,1]
	s_waitcnt vmcnt(1)
; __device__ __forceinline__ void diff_attn_phase(const P& p_, int j, float lam_init, char* smem, bool dry = false) {
;     ...
; #pragma unroll
;         for (int et = 0; et < 4; ++et)
; #pragma unroll
;           for (int rg = 0; rg < 2; ++rg) {
;             const h8 sv = *(const h8*)(stash + et * 16 + rg * 8);
; #pragma unroll
;             for (int i = 0; i < 8; ++i) o[et][rg * 8 + i] = (float)sv[i] - lam_full * (o[et][rg * 8 + i] * inv);
;           }
;       }
;     }
;     float ss = 0.f;
; #pragma unroll
;     for (int et = 0; et < 4; ++et)
; #pragma unroll
;       for (int r = 0; r < 16; ++r) ss += o[et][r] * o[et][r];
	v_cvt_f32_f16_sdwa v11, v100 dst_sel:DWORD dst_unused:UNUSED_PAD src0_sel:WORD_1
	v_cvt_f32_f16_e32 v10, v100
	v_cvt_f32_f16_sdwa v107, v101 dst_sel:DWORD dst_unused:UNUSED_PAD src0_sel:WORD_1
	v_cvt_f32_f16_e32 v106, v101
	v_pk_fma_f32 v[64:65], v[132:133], v[12:13], v[10:11] neg_lo:[1,0,0] neg_hi:[1,0,0]
	s_nop 0
	v_mul_f32_e32 v10, v65, v65
	v_pk_fma_f32 v[104:105], v[64:65], v[64:65], v[10:11] op_sel_hi:[1,1,0]
	v_pk_fma_f32 v[66:67], v[132:133], v[66:67], v[106:107] neg_lo:[1,0,0] neg_hi:[1,0,0]
	global_load_dwordx4 v[10:13], v[134:135], off
	v_pk_fma_f32 v[100:101], v[66:67], v[66:67], v[104:105]
	v_mul_f32_e32 v104, v67, v67
	v_pk_add_f32 v[100:101], v[104:105], v[100:101] op_sel_hi:[0,1]
	v_cvt_f32_f16_sdwa v105, v102 dst_sel:DWORD dst_unused:UNUSED_PAD src0_sel:WORD_1
	v_cvt_f32_f16_e32 v104, v102
	v_pk_fma_f32 v[68:69], v[132:133], v[68:69], v[104:105] neg_lo:[1,0,0] neg_hi:[1,0,0]
	v_cvt_f32_f16_sdwa v105, v103 dst_sel:DWORD dst_unused:UNUSED_PAD src0_sel:WORD_1
	v_cvt_f32_f16_e32 v104, v103
	v_pk_fma_f32 v[100:101], v[68:69], v[68:69], v[100:101]
	v_mul_f32_e32 v102, v69, v69
	v_pk_add_f32 v[100:101], v[102:103], v[100:101] op_sel_hi:[0,1]
	v_pk_fma_f32 v[70:71], v[132:133], v[70:71], v[104:105] neg_lo:[1,0,0] neg_hi:[1,0,0]
	s_nop 0
	v_pk_fma_f32 v[100:101], v[70:71], v[70:71], v[100:101]
	v_mul_f32_e32 v102, v71, v71
	v_pk_add_f32 v[100:101], v[102:103], v[100:101] op_sel_hi:[0,1]
	s_waitcnt vmcnt(1)
	v_cvt_f32_f16_sdwa v103, v96 dst_sel:DWORD dst_unused:UNUSED_PAD src0_sel:WORD_1
	v_cvt_f32_f16_e32 v102, v96
	v_pk_fma_f32 v[72:73], v[132:133], v[72:73], v[102:103] neg_lo:[1,0,0] neg_hi:[1,0,0]
	v_cvt_f32_f16_sdwa v103, v97 dst_sel:DWORD dst_unused:UNUSED_PAD src0_sel:WORD_1
	v_cvt_f32_f16_e32 v102, v97
	v_pk_fma_f32 v[100:101], v[72:73], v[72:73], v[100:101]
	v_mul_f32_e32 v96, v73, v73
	v_pk_add_f32 v[100:101], v[96:97], v[100:101] op_sel_hi:[0,1]
	v_pk_fma_f32 v[74:75], v[132:133], v[74:75], v[102:103] neg_lo:[1,0,0] neg_hi:[1,0,0]
	s_nop 0
	v_pk_fma_f32 v[96:97], v[74:75], v[74:75], v[100:101]
	v_mul_f32_e32 v100, v75, v75
	v_pk_add_f32 v[96:97], v[100:101], v[96:97] op_sel_hi:[0,1]
	v_cvt_f32_f16_sdwa v101, v98 dst_sel:DWORD dst_unused:UNUSED_PAD src0_sel:WORD_1
	v_cvt_f32_f16_e32 v100, v98
	v_pk_fma_f32 v[76:77], v[132:133], v[76:77], v[100:101] neg_lo:[1,0,0] neg_hi:[1,0,0]
	v_cvt_f32_f16_sdwa v101, v99 dst_sel:DWORD dst_unused:UNUSED_PAD src0_sel:WORD_1
	v_cvt_f32_f16_e32 v100, v99
	v_pk_fma_f32 v[96:97], v[76:77], v[76:77], v[96:97]
	v_mul_f32_e32 v98, v77, v77
	v_pk_add_f32 v[96:97], v[98:99], v[96:97] op_sel_hi:[0,1]
	v_pk_fma_f32 v[78:79], v[132:133], v[78:79], v[100:101] neg_lo:[1,0,0] neg_hi:[1,0,0]
	s_nop 0
	v_pk_fma_f32 v[96:97], v[78:79], v[78:79], v[96:97]
	v_mul_f32_e32 v98, v79, v79
	v_pk_add_f32 v[96:97], v[98:99], v[96:97] op_sel_hi:[0,1]
	v_cvt_f32_f16_sdwa v99, v92 dst_sel:DWORD dst_unused:UNUSED_PAD src0_sel:WORD_1
	v_cvt_f32_f16_e32 v98, v92
	v_pk_fma_f32 v[48:49], v[132:133], v[48:49], v[98:99] neg_lo:[1,0,0] neg_hi:[1,0,0]
	v_cvt_f32_f16_sdwa v99, v93 dst_sel:DWORD dst_unused:UNUSED_PAD src0_sel:WORD_1
	v_cvt_f32_f16_e32 v98, v93
	v_pk_fma_f32 v[96:97], v[48:49], v[48:49], v[96:97]
	v_mul_f32_e32 v92, v49, v49
	v_pk_add_f32 v[96:97], v[92:93], v[96:97] op_sel_hi:[0,1]
	v_pk_fma_f32 v[50:51], v[132:133], v[50:51], v[98:99] neg_lo:[1,0,0] neg_hi:[1,0,0]
	s_nop 0
	v_pk_fma_f32 v[92:93], v[50:51], v[50:51], v[96:97]
	v_mul_f32_e32 v96, v51, v51
	v_pk_add_f32 v[92:93], v[96:97], v[92:93] op_sel_hi:[0,1]
	v_cvt_f32_f16_sdwa v97, v94 dst_sel:DWORD dst_unused:UNUSED_PAD src0_sel:WORD_1
	v_cvt_f32_f16_e32 v96, v94
	v_pk_fma_f32 v[52:53], v[132:133], v[52:53], v[96:97] neg_lo:[1,0,0] neg_hi:[1,0,0]
	v_cvt_f32_f16_sdwa v97, v95 dst_sel:DWORD dst_unused:UNUSED_PAD src0_sel:WORD_1
	v_cvt_f32_f16_e32 v96, v95
	v_pk_fma_f32 v[92:93], v[52:53], v[52:53], v[92:93]
	v_mul_f32_e32 v94, v53, v53
	v_pk_add_f32 v[92:93], v[94:95], v[92:93] op_sel_hi:[0,1]
	v_pk_fma_f32 v[54:55], v[132:133], v[54:55], v[96:97] neg_lo:[1,0,0] neg_hi:[1,0,0]
	s_nop 0
	v_pk_fma_f32 v[92:93], v[54:55], v[54:55], v[92:93]
	v_mul_f32_e32 v94, v55, v55
	v_pk_add_f32 v[92:93], v[94:95], v[92:93] op_sel_hi:[0,1]
	v_cvt_f32_f16_sdwa v95, v88 dst_sel:DWORD dst_unused:UNUSED_PAD src0_sel:WORD_1
	v_cvt_f32_f16_e32 v94, v88
	v_pk_fma_f32 v[56:57], v[132:133], v[56:57], v[94:95] neg_lo:[1,0,0] neg_hi:[1,0,0]
	v_cvt_f32_f16_sdwa v95, v89 dst_sel:DWORD dst_unused:UNUSED_PAD src0_sel:WORD_1
	v_cvt_f32_f16_e32 v94, v89
	v_pk_fma_f32 v[92:93], v[56:57], v[56:57], v[92:93]
	v_mul_f32_e32 v88, v57, v57
	v_pk_add_f32 v[92:93], v[88:89], v[92:93] op_sel_hi:[0,1]
	v_pk_fma_f32 v[58:59], v[132:133], v[58:59], v[94:95] neg_lo:[1,0,0] neg_hi:[1,0,0]
	s_nop 0
	v_pk_fma_f32 v[88:89], v[58:59], v[58:59], v[92:93]
	v_mul_f32_e32 v92, v59, v59
	v_pk_add_f32 v[88:89], v[92:93], v[88:89] op_sel_hi:[0,1]
	v_cvt_f32_f16_sdwa v93, v90 dst_sel:DWORD dst_unused:UNUSED_PAD src0_sel:WORD_1
	v_cvt_f32_f16_e32 v92, v90
	v_pk_fma_f32 v[60:61], v[132:133], v[60:61], v[92:93] neg_lo:[1,0,0] neg_hi:[1,0,0]
	v_cvt_f32_f16_sdwa v93, v91 dst_sel:DWORD dst_unused:UNUSED_PAD src0_sel:WORD_1
	v_cvt_f32_f16_e32 v92, v91
	v_pk_fma_f32 v[88:89], v[60:61], v[60:61], v[88:89]
	v_mul_f32_e32 v90, v61, v61
	v_pk_add_f32 v[88:89], v[90:91], v[88:89] op_sel_hi:[0,1]
	v_pk_fma_f32 v[62:63], v[132:133], v[62:63], v[92:93] neg_lo:[1,0,0] neg_hi:[1,0,0]
	s_nop 0
	v_pk_fma_f32 v[88:89], v[62:63], v[62:63], v[88:89]
	v_mul_f32_e32 v90, v63, v63
	v_pk_add_f32 v[88:89], v[90:91], v[88:89] op_sel_hi:[0,1]
	v_cvt_f32_f16_sdwa v91, v84 dst_sel:DWORD dst_unused:UNUSED_PAD src0_sel:WORD_1
	v_cvt_f32_f16_e32 v90, v84
; __device__ __forceinline__ void diff_attn_phase(const P& p_, int j, float lam_init, char* smem, bool dry = false) {
;     ...
;     float ss = 0.f;
; #pragma unroll
;     for (int et = 0; et < 4; ++et)
; #pragma unroll
;       for (int r = 0; r < 16; ++r) ss += o[et][r] * o[et][r];
;     ss = xhalf_sum(ss);
;     if (dry && ss != 12345.678f) continue;
;     const float rs = rsqrtf(ss * (1.f / 128.f) + 1e-5f) * (1.f - lam_init);
	v_pk_fma_f32 v[32:33], v[132:133], v[32:33], v[90:91] neg_lo:[1,0,0] neg_hi:[1,0,0]
	v_cvt_f32_f16_sdwa v91, v85 dst_sel:DWORD dst_unused:UNUSED_PAD src0_sel:WORD_1
	v_cvt_f32_f16_e32 v90, v85
	v_pk_fma_f32 v[88:89], v[32:33], v[32:33], v[88:89]
	v_mul_f32_e32 v84, v33, v33
	v_pk_add_f32 v[88:89], v[84:85], v[88:89] op_sel_hi:[0,1]
	v_pk_fma_f32 v[34:35], v[132:133], v[34:35], v[90:91] neg_lo:[1,0,0] neg_hi:[1,0,0]
	s_nop 0
	v_pk_fma_f32 v[84:85], v[34:35], v[34:35], v[88:89]
	v_mul_f32_e32 v88, v35, v35
	v_pk_add_f32 v[84:85], v[88:89], v[84:85] op_sel_hi:[0,1]
	v_cvt_f32_f16_sdwa v89, v86 dst_sel:DWORD dst_unused:UNUSED_PAD src0_sel:WORD_1
	v_cvt_f32_f16_e32 v88, v86
	v_pk_fma_f32 v[36:37], v[132:133], v[36:37], v[88:89] neg_lo:[1,0,0] neg_hi:[1,0,0]
	v_cvt_f32_f16_sdwa v89, v87 dst_sel:DWORD dst_unused:UNUSED_PAD src0_sel:WORD_1
	v_cvt_f32_f16_e32 v88, v87
	v_pk_fma_f32 v[84:85], v[36:37], v[36:37], v[84:85]
	v_mul_f32_e32 v86, v37, v37
	v_pk_add_f32 v[84:85], v[86:87], v[84:85] op_sel_hi:[0,1]
	v_pk_fma_f32 v[38:39], v[132:133], v[38:39], v[88:89] neg_lo:[1,0,0] neg_hi:[1,0,0]
	s_nop 0
	v_pk_fma_f32 v[84:85], v[38:39], v[38:39], v[84:85]
	v_mul_f32_e32 v86, v39, v39
	v_pk_add_f32 v[84:85], v[86:87], v[84:85] op_sel_hi:[0,1]
	v_cvt_f32_f16_sdwa v87, v80 dst_sel:DWORD dst_unused:UNUSED_PAD src0_sel:WORD_1
	v_cvt_f32_f16_e32 v86, v80
	v_pk_fma_f32 v[40:41], v[132:133], v[40:41], v[86:87] neg_lo:[1,0,0] neg_hi:[1,0,0]
	v_cvt_f32_f16_sdwa v87, v81 dst_sel:DWORD dst_unused:UNUSED_PAD src0_sel:WORD_1
	v_cvt_f32_f16_e32 v86, v81
	v_pk_fma_f32 v[84:85], v[40:41], v[40:41], v[84:85]
	v_mul_f32_e32 v80, v41, v41
	v_pk_add_f32 v[84:85], v[80:81], v[84:85] op_sel_hi:[0,1]
	v_pk_fma_f32 v[42:43], v[132:133], v[42:43], v[86:87] neg_lo:[1,0,0] neg_hi:[1,0,0]
	s_nop 0
	v_pk_fma_f32 v[80:81], v[42:43], v[42:43], v[84:85]
	v_mul_f32_e32 v84, v43, v43
	v_pk_add_f32 v[80:81], v[84:85], v[80:81] op_sel_hi:[0,1]
	v_cvt_f32_f16_sdwa v85, v82 dst_sel:DWORD dst_unused:UNUSED_PAD src0_sel:WORD_1
	v_cvt_f32_f16_e32 v84, v82
	v_pk_fma_f32 v[44:45], v[132:133], v[44:45], v[84:85] neg_lo:[1,0,0] neg_hi:[1,0,0]
	v_cvt_f32_f16_sdwa v85, v83 dst_sel:DWORD dst_unused:UNUSED_PAD src0_sel:WORD_1
	v_cvt_f32_f16_e32 v84, v83
	v_pk_fma_f32 v[80:81], v[44:45], v[44:45], v[80:81]
	v_mul_f32_e32 v82, v45, v45
	v_pk_add_f32 v[80:81], v[82:83], v[80:81] op_sel_hi:[0,1]
	v_pk_fma_f32 v[46:47], v[132:133], v[46:47], v[84:85] neg_lo:[1,0,0] neg_hi:[1,0,0]
	s_nop 0
	v_pk_fma_f32 v[80:81], v[46:47], v[46:47], v[80:81]
	v_mul_f32_e32 v82, v47, v47
	v_pk_add_f32 v[80:81], v[82:83], v[80:81] op_sel_hi:[0,1]
	v_cvt_f32_f16_sdwa v83, v6 dst_sel:DWORD dst_unused:UNUSED_PAD src0_sel:WORD_1
	v_cvt_f32_f16_e32 v82, v6
	v_pk_fma_f32 v[16:17], v[132:133], v[16:17], v[82:83] neg_lo:[1,0,0] neg_hi:[1,0,0]
	v_cvt_f32_f16_sdwa v83, v7 dst_sel:DWORD dst_unused:UNUSED_PAD src0_sel:WORD_1
	v_cvt_f32_f16_e32 v82, v7
	v_pk_fma_f32 v[80:81], v[16:17], v[16:17], v[80:81]
	v_mul_f32_e32 v6, v17, v17
	v_pk_add_f32 v[80:81], v[6:7], v[80:81] op_sel_hi:[0,1]
	v_pk_mul_f32 v[6:7], v[0:1], v[18:19] op_sel_hi:[0,1]
	v_pk_fma_f32 v[6:7], v[132:133], v[6:7], v[82:83] neg_lo:[1,0,0] neg_hi:[1,0,0]
	s_nop 0
	v_pk_fma_f32 v[18:19], v[6:7], v[6:7], v[80:81]
	v_mul_f32_e32 v80, v7, v7
	v_pk_add_f32 v[80:81], v[80:81], v[18:19] op_sel_hi:[0,1]
	v_cvt_f32_f16_sdwa v19, v8 dst_sel:DWORD dst_unused:UNUSED_PAD src0_sel:WORD_1
	v_cvt_f32_f16_e32 v18, v8
	v_pk_fma_f32 v[18:19], v[132:133], v[20:21], v[18:19] neg_lo:[1,0,0] neg_hi:[1,0,0]
	s_nop 0
	v_pk_fma_f32 v[20:21], v[18:19], v[18:19], v[80:81]
	v_cvt_f32_f16_sdwa v81, v9 dst_sel:DWORD dst_unused:UNUSED_PAD src0_sel:WORD_1
	v_cvt_f32_f16_e32 v80, v9
	v_mul_f32_e32 v8, v19, v19
	v_pk_add_f32 v[20:21], v[8:9], v[20:21] op_sel_hi:[0,1]
	v_pk_mul_f32 v[8:9], v[0:1], v[22:23] op_sel_hi:[0,1]
	v_pk_fma_f32 v[8:9], v[132:133], v[8:9], v[80:81] neg_lo:[1,0,0] neg_hi:[1,0,0]
	s_nop 0
	v_pk_fma_f32 v[20:21], v[8:9], v[8:9], v[20:21]
	v_mul_f32_e32 v22, v9, v9
	v_pk_add_f32 v[22:23], v[22:23], v[20:21] op_sel_hi:[0,1]
	v_cvt_f32_f16_sdwa v21, v2 dst_sel:DWORD dst_unused:UNUSED_PAD src0_sel:WORD_1
	v_cvt_f32_f16_e32 v20, v2
	v_pk_fma_f32 v[20:21], v[132:133], v[24:25], v[20:21] neg_lo:[1,0,0] neg_hi:[1,0,0]
	v_cvt_f32_f16_sdwa v25, v3 dst_sel:DWORD dst_unused:UNUSED_PAD src0_sel:WORD_1
	v_cvt_f32_f16_e32 v24, v3
	v_pk_fma_f32 v[22:23], v[20:21], v[20:21], v[22:23]
	v_mul_f32_e32 v2, v21, v21
	v_pk_add_f32 v[22:23], v[2:3], v[22:23] op_sel_hi:[0,1]
	v_pk_mul_f32 v[2:3], v[0:1], v[26:27] op_sel_hi:[0,1]
	v_pk_fma_f32 v[2:3], v[132:133], v[2:3], v[24:25] neg_lo:[1,0,0] neg_hi:[1,0,0]
	v_pk_mul_f32 v[26:27], v[0:1], v[28:29] op_sel_hi:[0,1]
	v_pk_fma_f32 v[22:23], v[2:3], v[2:3], v[22:23]
	v_mul_f32_e32 v24, v3, v3
	v_pk_add_f32 v[24:25], v[24:25], v[22:23] op_sel_hi:[0,1]
	v_cvt_f32_f16_sdwa v23, v4 dst_sel:DWORD dst_unused:UNUSED_PAD src0_sel:WORD_1
	v_cvt_f32_f16_e32 v22, v4
	v_pk_fma_f32 v[22:23], v[132:133], v[26:27], v[22:23] neg_lo:[1,0,0] neg_hi:[1,0,0]
	v_cvt_f32_f16_sdwa v27, v5 dst_sel:DWORD dst_unused:UNUSED_PAD src0_sel:WORD_1
	v_cvt_f32_f16_e32 v26, v5
	v_pk_fma_f32 v[24:25], v[22:23], v[22:23], v[24:25]
	v_mul_f32_e32 v4, v23, v23
	v_pk_add_f32 v[24:25], v[4:5], v[24:25] op_sel_hi:[0,1]
	v_pk_mul_f32 v[4:5], v[0:1], v[30:31] op_sel_hi:[0,1]
	v_pk_fma_f32 v[4:5], v[132:133], v[4:5], v[26:27] neg_lo:[1,0,0] neg_hi:[1,0,0]
	s_nop 0
	v_pk_fma_f32 v[24:25], v[4:5], v[4:5], v[24:25]
	v_mul_f32_e32 v0, v5, v5
	v_pk_add_f32 v[24:25], v[0:1], v[24:25] op_sel_hi:[0,1]
	v_mov_b32_e32 v0, v24
	s_nop 1
	v_permlane32_swap_b32_e32 v24, v0
	v_add_f32_e32 v0, v24, v0
	v_fmamk_f32 v0, v0, 0x3c000000, v224
	v_cmp_gt_f32_e32 vcc, s2, v0
	v_mul_f32_e32 v24, 0x4b800000, v0
	s_nop 0
	v_cndmask_b32_e32 v0, v0, v24, vcc
	v_rsq_f32_e32 v0, v0
	s_nop 0
	v_mul_f32_e32 v24, 0x45800000, v0
	v_cndmask_b32_e32 v0, v0, v24, vcc
	v_mul_f32_e32 v0, v168, v0
	v_pk_mul_f32 v[24:25], v[64:65], v[0:1] op_sel_hi:[1,0]
	v_pk_mul_f32 v[16:17], v[16:17], v[0:1] op_sel_hi:[1,0]
	s_waitcnt vmcnt(0)
; __device__ __forceinline__ void diff_attn_phase(const P& p_, int j, float lam_init, char* smem, bool dry = false) {
;     ...
;     const float rs = rsqrtf(ss * (1.f / 128.f) + 1e-5f) * (1.f - lam_init);
; #pragma unroll
;     for (int et = 0; et < 4; ++et)
; #pragma unroll
;       for (int rg = 0; rg < 4; ++rg) {
;         int e0 = et * 32 + 8 * rg + 4 * hi;
;         h4 ov;
; #pragma unroll
;         for (int i = 0; i < 4; ++i) ov[i] = (h16)(o[et][rg * 4 + i] * rs * subln[e0 + i]);
;         *(h4*)(O + (size_t)tok * 1024 + h * 128 + e0) = ov;
;       }
	v_pk_mul_f32 v[10:11], v[10:11], v[24:25]
	v_pk_mul_f32 v[24:25], v[66:67], v[0:1] op_sel_hi:[1,0]
	v_cvt_pk_f16_f32 v10, v10, v11
	v_pk_mul_f32 v[12:13], v[12:13], v[24:25]
	v_pk_mul_f32 v[24:25], v[68:69], v[0:1] op_sel_hi:[1,0]
	v_cvt_pk_f16_f32 v11, v12, v13
	global_store_dwordx2 v[14:15], v[10:11], off
	global_load_dwordx4 v[10:13], v[134:135], off offset:32
	v_pk_mul_f32 v[6:7], v[6:7], v[0:1] op_sel_hi:[1,0]
	v_pk_mul_f32 v[8:9], v[8:9], v[0:1] op_sel_hi:[1,0]
	v_pk_mul_f32 v[2:3], v[2:3], v[0:1] op_sel_hi:[1,0]
	v_pk_mul_f32 v[4:5], v[4:5], v[0:1] op_sel_hi:[1,0]
	s_waitcnt vmcnt(0)
	v_pk_mul_f32 v[10:11], v[10:11], v[24:25]
	v_pk_mul_f32 v[24:25], v[70:71], v[0:1] op_sel_hi:[1,0]
	v_cvt_pk_f16_f32 v10, v10, v11
	v_pk_mul_f32 v[12:13], v[12:13], v[24:25]
	v_pk_mul_f32 v[24:25], v[72:73], v[0:1] op_sel_hi:[1,0]
	v_cvt_pk_f16_f32 v11, v12, v13
	global_store_dwordx2 v[14:15], v[10:11], off offset:16
	global_load_dwordx4 v[10:13], v[134:135], off offset:64
	s_waitcnt vmcnt(0)
	v_pk_mul_f32 v[10:11], v[10:11], v[24:25]
	v_pk_mul_f32 v[24:25], v[74:75], v[0:1] op_sel_hi:[1,0]
	v_cvt_pk_f16_f32 v10, v10, v11
	v_pk_mul_f32 v[12:13], v[24:25], v[12:13]
	v_pk_mul_f32 v[24:25], v[76:77], v[0:1] op_sel_hi:[1,0]
	v_cvt_pk_f16_f32 v11, v12, v13
	global_store_dwordx2 v[14:15], v[10:11], off offset:32
	global_load_dwordx4 v[10:13], v[134:135], off offset:96
	s_waitcnt vmcnt(0)
	v_pk_mul_f32 v[10:11], v[24:25], v[10:11]
	v_pk_mul_f32 v[24:25], v[78:79], v[0:1] op_sel_hi:[1,0]
	v_cvt_pk_f16_f32 v10, v10, v11
	v_pk_mul_f32 v[12:13], v[24:25], v[12:13]
	v_pk_mul_f32 v[24:25], v[48:49], v[0:1] op_sel_hi:[1,0]
	v_cvt_pk_f16_f32 v11, v12, v13
	global_store_dwordx2 v[14:15], v[10:11], off offset:48
	global_load_dwordx4 v[10:13], v[134:135], off offset:128
	s_waitcnt vmcnt(0)
	v_pk_mul_f32 v[10:11], v[24:25], v[10:11]
	v_pk_mul_f32 v[24:25], v[50:51], v[0:1] op_sel_hi:[1,0]
	v_cvt_pk_f16_f32 v10, v10, v11
	v_pk_mul_f32 v[12:13], v[24:25], v[12:13]
	v_pk_mul_f32 v[24:25], v[52:53], v[0:1] op_sel_hi:[1,0]
	v_cvt_pk_f16_f32 v11, v12, v13
	global_store_dwordx2 v[14:15], v[10:11], off offset:64
	global_load_dwordx4 v[10:13], v[134:135], off offset:160
	s_waitcnt vmcnt(0)
	v_pk_mul_f32 v[10:11], v[24:25], v[10:11]
	v_pk_mul_f32 v[24:25], v[54:55], v[0:1] op_sel_hi:[1,0]
	v_cvt_pk_f16_f32 v10, v10, v11
	v_pk_mul_f32 v[12:13], v[24:25], v[12:13]
	v_pk_mul_f32 v[24:25], v[56:57], v[0:1] op_sel_hi:[1,0]
	v_cvt_pk_f16_f32 v11, v12, v13
	global_store_dwordx2 v[14:15], v[10:11], off offset:80
	global_load_dwordx4 v[10:13], v[134:135], off offset:192
	s_waitcnt vmcnt(0)
	v_pk_mul_f32 v[10:11], v[24:25], v[10:11]
	v_pk_mul_f32 v[24:25], v[58:59], v[0:1] op_sel_hi:[1,0]
	v_cvt_pk_f16_f32 v10, v10, v11
	v_pk_mul_f32 v[12:13], v[24:25], v[12:13]
	v_pk_mul_f32 v[24:25], v[60:61], v[0:1] op_sel_hi:[1,0]
	v_cvt_pk_f16_f32 v11, v12, v13
	global_store_dwordx2 v[14:15], v[10:11], off offset:96
	global_load_dwordx4 v[10:13], v[134:135], off offset:224
	s_waitcnt vmcnt(0)
	v_pk_mul_f32 v[10:11], v[24:25], v[10:11]
	v_pk_mul_f32 v[24:25], v[62:63], v[0:1] op_sel_hi:[1,0]
	v_cvt_pk_f16_f32 v10, v10, v11
	v_pk_mul_f32 v[12:13], v[24:25], v[12:13]
	v_pk_mul_f32 v[24:25], v[32:33], v[0:1] op_sel_hi:[1,0]
	v_cvt_pk_f16_f32 v11, v12, v13
	global_store_dwordx2 v[14:15], v[10:11], off offset:112
	global_load_dwordx4 v[10:13], v[134:135], off offset:256
	s_waitcnt vmcnt(0)
	v_pk_mul_f32 v[10:11], v[24:25], v[10:11]
	v_pk_mul_f32 v[24:25], v[34:35], v[0:1] op_sel_hi:[1,0]
	v_cvt_pk_f16_f32 v10, v10, v11
	v_pk_mul_f32 v[12:13], v[24:25], v[12:13]
	v_pk_mul_f32 v[24:25], v[36:37], v[0:1] op_sel_hi:[1,0]
	v_cvt_pk_f16_f32 v11, v12, v13
	global_store_dwordx2 v[14:15], v[10:11], off offset:128
	global_load_dwordx4 v[10:13], v[134:135], off offset:288
	s_waitcnt vmcnt(0)
	v_pk_mul_f32 v[10:11], v[24:25], v[10:11]
	v_pk_mul_f32 v[24:25], v[38:39], v[0:1] op_sel_hi:[1,0]
	v_cvt_pk_f16_f32 v10, v10, v11
	v_pk_mul_f32 v[12:13], v[24:25], v[12:13]
	v_pk_mul_f32 v[24:25], v[40:41], v[0:1] op_sel_hi:[1,0]
	v_cvt_pk_f16_f32 v11, v12, v13
	global_store_dwordx2 v[14:15], v[10:11], off offset:144
	global_load_dwordx4 v[10:13], v[134:135], off offset:320
	s_waitcnt vmcnt(0)
	v_pk_mul_f32 v[10:11], v[24:25], v[10:11]
	v_pk_mul_f32 v[24:25], v[42:43], v[0:1] op_sel_hi:[1,0]
	v_cvt_pk_f16_f32 v10, v10, v11
	v_pk_mul_f32 v[12:13], v[24:25], v[12:13]
	v_pk_mul_f32 v[24:25], v[44:45], v[0:1] op_sel_hi:[1,0]
	v_cvt_pk_f16_f32 v11, v12, v13
	global_store_dwordx2 v[14:15], v[10:11], off offset:160
	global_load_dwordx4 v[10:13], v[134:135], off offset:352
	s_waitcnt vmcnt(0)
	v_pk_mul_f32 v[10:11], v[24:25], v[10:11]
	v_pk_mul_f32 v[24:25], v[46:47], v[0:1] op_sel_hi:[1,0]
	v_cvt_pk_f16_f32 v10, v10, v11
	v_pk_mul_f32 v[12:13], v[24:25], v[12:13]
	s_nop 0
	v_cvt_pk_f16_f32 v11, v12, v13
	global_store_dwordx2 v[14:15], v[10:11], off offset:176
	global_load_dwordx4 v[10:13], v[134:135], off offset:384
	s_waitcnt vmcnt(0)
	v_pk_mul_f32 v[10:11], v[16:17], v[10:11]
	v_pk_mul_f32 v[6:7], v[6:7], v[12:13]
	v_cvt_pk_f16_f32 v10, v10, v11
	v_cvt_pk_f16_f32 v11, v6, v7
	global_store_dwordx2 v[14:15], v[10:11], off offset:192
	global_load_dwordx4 v[10:13], v[134:135], off offset:416
	v_pk_mul_f32 v[6:7], v[18:19], v[0:1] op_sel_hi:[1,0]
	s_waitcnt vmcnt(0)
	v_pk_mul_f32 v[8:9], v[8:9], v[12:13]
	v_pk_mul_f32 v[6:7], v[6:7], v[10:11]
	v_pk_mul_f32 v[10:11], v[20:21], v[0:1] op_sel_hi:[1,0]
	v_cvt_pk_f16_f32 v6, v6, v7
	v_cvt_pk_f16_f32 v7, v8, v9
	global_store_dwordx2 v[14:15], v[6:7], off offset:208
	global_load_dwordx4 v[6:9], v[134:135], off offset:448
	s_waitcnt vmcnt(0)
	v_pk_mul_f32 v[6:7], v[10:11], v[6:7]
	v_pk_mul_f32 v[2:3], v[2:3], v[8:9]
	v_cvt_pk_f16_f32 v6, v6, v7
	v_cvt_pk_f16_f32 v7, v2, v3
	global_store_dwordx2 v[14:15], v[6:7], off offset:224
	global_load_dwordx4 v[6:9], v[134:135], off offset:480
	v_pk_mul_f32 v[2:3], v[22:23], v[0:1] op_sel_hi:[1,0]
	s_waitcnt vmcnt(0)
	v_pk_mul_f32 v[4:5], v[4:5], v[8:9]
	v_pk_mul_f32 v[2:3], v[2:3], v[6:7]
	s_nop 0
	v_cvt_pk_f16_f32 v2, v2, v3
	v_cvt_pk_f16_f32 v3, v4, v5
	global_store_dwordx2 v[14:15], v[2:3], off offset:240
	s_cbranch_scc1 .LBB0_1109
; __device__ __forceinline__ int tidx() { int t = threadIdx.x; asm volatile("" : "+v"(t)); return t; }
; __device__ __forceinline__ int bidx() { int t = blockIdx.x; asm volatile("" : "+s"(t)); return t; }
; template <int EQK, int EV, bool PF, class KP, class SC>
; __device__ __forceinline__ void flash_core(f16v (&o)[EV / 32], float& m_run, float& l_run, const h8 (&qf)[EQK / 16],
;                                            int kt0, int kt1, const KP& kp, const SC& sc, char* smem) {
;     ...
;   auto gload = [&](int kt) {
; #pragma unroll
;     for (int i = 0; i < NKC; ++i) { int c = tid + 256 * i, row = c / KCH, kc = (c - row * KCH) * 8; rk[i] = *(const h8*)(kp.kptr(kt, row) + kc); }
; #pragma unroll
;     for (int i = 0; i < NVC; ++i) { int c = tid + 256 * i, e = c >> 3, kc = (c & 7) * 8; rv[i] = *(const h8*)(kp.vptr(kt, e) + kc); }
;   };
; __device__ __forceinline__ void diff_attn_phase(const P& p_, int j, float lam_init, char* smem, bool dry = false) {
;     ...
;   for (int item = bidx(); item < 1024; item += gridDim.x) {
;     const int b = item >> 8, h = (item >> 5) & 7, qt = item & 31;
;     const int tok = b * S_ + qt * 128 + qslot;
;     f16v o[4];
;     h16* stash = (h16*)(p.ws + S_STASH) + ((size_t)bidx() * 256 + tidx()) * 64;
; #pragma unroll
;     for (int c = 0; c < 2; ++c) {
;       h8 qf[4];
; #pragma unroll
;       for (int d = 0; d < 4; ++d) qf[d] = *(const h8*)(QK + (size_t)tok * 2048 + h * 128 + c * 64 + d * 16 + hi * 8) * (h16)0.125f;
; #pragma unroll
;       for (int et = 0; et < 4; ++et)
; #pragma unroll
;         for (int r = 0; r < 16; ++r) o[et][r] = 0.f;
;       float m_run = -1e30f, l_run = 0.f;
;       KPDiff kp{QK + (size_t)b * S_ * 2048 + 1024 + h * 128 + c * 64, VT + (size_t)(h * 128) * T_ + b * S_};
;       SCDiff sc{exp2f(-(float)(h + 1)), qt * 128};
.LBB0_1095:
	v_bfe_u32 v253, v180, 5, 1
	v_lshlrev_b32_e32 v253, 3, v253
	v_and_b32_e32 v252, 1, v180
	v_lshlrev_b32_e32 v252, 3, v252
	v_sub_u32_e32 v252, 0x2400, v252
	s_and_b32 s2, s0, 7
	s_lshl_b32 s2, s2, 6
	s_bfe_u32 s15, s0, 0x60003
	s_or_b32 s2, s2, s15
	s_and_b32 s15, s0, 0x200
	s_or_b32 s2, s2, s15
	s_ashr_i32 s14, s2, 8
	s_lshl_b32 s15, s2, 7
	s_lshl_b32 s16, s14, 12
	s_and_b32 s47, s15, 0xf80
	s_or_b32 s15, s16, s47
	v_add_u32_e32 v140, s15, v169
	v_ashrrev_i32_e32 v141, 31, v140
	s_bfe_u32 s2, s2, 0x30005
	v_lshlrev_b64 v[2:3], 12, v[140:141]
	s_lshl_b32 s88, s2, 8
	v_lshl_add_u64 v[2:3], s[10:11], 0, v[2:3]
	v_lshl_add_u64 v[2:3], v[2:3], 0, s[88:89]
	v_mov_b32_e32 v137, v1
	s_mov_b32 s40, s86
	v_mov_b32_e32 v142, v180
	v_lshl_add_u64 v[144:145], v[2:3], 0, v[136:137]
	s_ashr_i32 s15, s14, 31
	v_mov_b32_e32 v0, v180
	s_mov_b32 s48, s47
	s_lshl_b32 s33, s2, 22
	s_lshl_b32 s46, s2, 7
	s_lshl_b64 s[14:15], s[14:15], 24
	global_load_dwordx4 v[2:5], v[144:145], off
	global_load_dwordx4 v[6:9], v[144:145], off offset:32
	global_load_dwordx4 v[10:13], v[144:145], off offset:64
	global_load_dwordx4 v[14:17], v[144:145], off offset:96
	s_add_u32 s17, s10, s14
	v_add_u32_e32 v28, 0x100, v0
	v_ashrrev_i32_e32 v18, 31, v0
	v_ashrrev_i32_e32 v20, 31, v28
	s_addc_u32 s24, s11, s15
	v_lshrrev_b32_e32 v18, 29, v18
	v_lshrrev_b32_e32 v20, 29, v20
	s_add_u32 s34, s17, s88
	v_add_u32_e32 v18, v0, v18
	v_add_u32_e32 v20, v28, v20
	s_addc_u32 s35, s24, 0
	v_ashrrev_i32_e32 v42, 3, v18
	v_ashrrev_i32_e32 v50, 3, v20
	s_add_u32 s24, s1, s33
	v_lshlrev_b32_e32 v18, 6, v42
	v_lshlrev_b32_e32 v26, 3, v0
	v_lshlrev_b32_e32 v20, 6, v50
	v_lshlrev_b32_e32 v21, 3, v28
	s_addc_u32 s25, s4, 0
	s_ashr_i32 s17, s16, 31
	v_sub_u32_e32 v44, v26, v18
	v_ashrrev_i32_e32 v43, 31, v42
	v_sub_u32_e32 v52, v21, v20
	v_ashrrev_i32_e32 v51, 31, v50
	s_lshl_b64 s[16:17], s[16:17], 1
	v_lshlrev_b64 v[46:47], 12, v[42:43]
	v_ashrrev_i32_e32 v45, 31, v44
	v_lshlrev_b64 v[54:55], 12, v[50:51]
	v_ashrrev_i32_e32 v53, 31, v52
	v_ashrrev_i32_e32 v58, 3, v0
	v_ashrrev_i32_e32 v62, 3, v28
	v_add_u32_e32 v34, 0x200, v0
	s_add_u32 s24, s24, s16
	v_lshl_add_u64 v[18:19], s[34:35], 0, v[46:47]
	v_lshlrev_b64 v[48:49], 1, v[44:45]
	v_lshl_add_u64 v[20:21], s[34:35], 0, v[54:55]
	v_lshlrev_b64 v[56:57], 1, v[52:53]
	v_ashrrev_i32_e32 v59, 31, v58
	v_ashrrev_i32_e32 v63, 31, v62
	v_ashrrev_i32_e32 v66, 3, v34
	v_add_u32_e32 v38, 0x300, v0
	s_addc_u32 s25, s25, s17
	v_lshl_add_u64 v[18:19], v[18:19], 0, v[48:49]
	v_lshl_add_u64 v[22:23], v[20:21], 0, v[56:57]
	v_and_b32_e32 v29, 56, v26
	v_lshlrev_b64 v[60:61], 15, v[58:59]
	v_lshlrev_b64 v[64:65], 15, v[62:63]
	v_ashrrev_i32_e32 v67, 31, v66
	v_ashrrev_i32_e32 v70, 3, v38
	s_barrier
; template <int EQK, int EV, bool PF, class KP, class SC>
; __device__ __forceinline__ void flash_core(f16v (&o)[EV / 32], float& m_run, float& l_run, const h8 (&qf)[EQK / 16],
;                                            int kt0, int kt1, const KP& kp, const SC& sc, char* smem) {
;     ...
;   auto lstore = [&](int buf) {
;     h16* sK = base + buf * BUFH; h16* sV = sK + 64 * KLD;
; #pragma unroll
;     for (int i = 0; i < NKC; ++i) { int c = tid + 256 * i, row = c / KCH, kc = (c - row * KCH) * 8; *(h8*)(sK + row * KLD + kc) = rk[i]; }
; #pragma unroll
;     for (int i = 0; i < NVC; ++i) { int c = tid + 256 * i, e = c >> 3, kc = (c & 7) * 8; *(h8*)(sV + e * VLD + kc) = rv[i]; }
;   };
;   __syncthreads();
;   gload(kt0); lstore(0);
;   __syncthreads();
; __device__ __forceinline__ void diff_attn_phase(const P& p_, int j, float lam_init, char* smem, bool dry = false) {
;     ...
;       h8 qf[4];
; #pragma unroll
;       for (int d = 0; d < 4; ++d) qf[d] = *(const h8*)(QK + (size_t)tok * 2048 + h * 128 + c * 64 + d * 16 + hi * 8) * (h16)0.125f;
; #pragma unroll
;       for (int et = 0; et < 4; ++et)
; #pragma unroll
;         for (int r = 0; r < 16; ++r) o[et][r] = 0.f;
;       float m_run = -1e30f, l_run = 0.f;
;       KPDiff kp{QK + (size_t)b * S_ * 2048 + 1024 + h * 128 + c * 64, VT + (size_t)(h * 128) * T_ + b * S_};
;       SCDiff sc{exp2f(-(float)(h + 1)), qt * 128};
;       flash_core<64, 128, true>(o, m_run, l_run, qf, 0, 64, kp, sc, smem);
	global_load_dwordx4 v[18:21], v[18:19], off offset:2048
	s_nop 0
	global_load_dwordx4 v[22:25], v[22:23], off offset:2048
	v_lshl_add_u64 v[26:27], s[24:25], 0, v[60:61]
	v_lshlrev_b32_e32 v146, 1, v29
	v_mov_b32_e32 v147, v1
	v_lshl_add_u64 v[28:29], s[24:25], 0, v[64:65]
	v_lshlrev_b64 v[68:69], 15, v[66:67]
	v_ashrrev_i32_e32 v71, 31, v70
	v_lshl_add_u64 v[26:27], v[26:27], 0, v[146:147]
	v_lshl_add_u64 v[30:31], v[28:29], 0, v[146:147]
	v_lshl_add_u64 v[34:35], s[24:25], 0, v[68:69]
	v_lshlrev_b64 v[72:73], 15, v[70:71]
	global_load_dwordx4 v[26:29], v[26:27], off
	s_nop 0
	global_load_dwordx4 v[30:33], v[30:31], off
	v_lshl_add_u64 v[34:35], v[34:35], 0, v[146:147]
	v_lshl_add_u64 v[38:39], s[24:25], 0, v[72:73]
	global_load_dwordx4 v[34:37], v[34:35], off
	v_lshl_add_u64 v[38:39], v[38:39], 0, v[146:147]
	global_load_dwordx4 v[38:41], v[38:39], off
	s_add_i32 s2, s2, 1
	v_cvt_f32_ubyte0_e32 v43, s2
	s_mov_b32 s2, 0x42fc0000
	v_cmp_lt_f32_e32 vcc, s2, v43
	s_movk_i32 s3, 0x3000
	v_lshlrev_b32_e32 v173, 1, v44
	v_cndmask_b32_e32 v45, 0, v227, vcc
	s_waitcnt vmcnt(9)
	v_pk_mul_f16 v127, v5, s3 op_sel_hi:[1,0]
	v_pk_mul_f16 v126, v4, s3 op_sel_hi:[1,0]
	v_pk_mul_f16 v125, v3, s3 op_sel_hi:[1,0]
	v_pk_mul_f16 v124, v2, s3 op_sel_hi:[1,0]
	s_waitcnt vmcnt(8)
	v_pk_mul_f16 v123, v9, s3 op_sel_hi:[1,0]
	v_pk_mul_f16 v122, v8, s3 op_sel_hi:[1,0]
	v_pk_mul_f16 v121, v7, s3 op_sel_hi:[1,0]
	v_pk_mul_f16 v120, v6, s3 op_sel_hi:[1,0]
	s_waitcnt vmcnt(7)
	v_pk_mul_f16 v119, v13, s3 op_sel_hi:[1,0]
	v_pk_mul_f16 v118, v12, s3 op_sel_hi:[1,0]
	v_pk_mul_f16 v117, v11, s3 op_sel_hi:[1,0]
	v_pk_mul_f16 v116, v10, s3 op_sel_hi:[1,0]
	s_waitcnt vmcnt(6)
	v_pk_mul_f16 v115, v17, s3 op_sel_hi:[1,0]
	v_pk_mul_f16 v114, v16, s3 op_sel_hi:[1,0]
	v_pk_mul_f16 v113, v15, s3 op_sel_hi:[1,0]
	v_pk_mul_f16 v112, v14, s3 op_sel_hi:[1,0]
	s_movk_i32 s3, 0x48
	v_sub_f32_e32 v43, v45, v43
	v_ashrrev_i32_e32 v3, 1, v0
	v_mul_lo_u32 v172, v42, s3
	v_exp_f32_e32 v43, v43
	v_and_b32_e32 v171, 0xffffffe0, v3
	v_lshl_add_u32 v3, v172, 1, v173
	v_mul_lo_u32 v174, v50, s3
	v_lshlrev_b32_e32 v175, 1, v52
	v_mul_lo_u32 v182, v58, s3
	s_and_b64 s[36:37], vcc, exec
	v_mul_lo_u32 v183, v62, s3
	s_cselect_b32 s36, 0xffffffc0, 0
	v_bfe_u32 v2, v0, 5, 1
	v_mul_lo_u32 v184, v66, s3
	v_ldexp_f32 v137, v43, s36
	v_and_b32_e32 v170, 31, v0
	v_mul_lo_u32 v185, v70, s3
	v_lshlrev_b32_e32 v16, 3, v2
	v_lshlrev_b32_e32 v147, 2, v2
	v_add_u32_e32 v2, s48, v171
	s_add_u32 s36, s33, 0xd100080
	v_or_b32_e32 v2, v2, v170
	s_addc_u32 s37, 0, 0
	v_lshlrev_b32_e32 v0, 4, v0
	v_sub_u32_e32 v187, v2, v147
	v_and_b32_e32 v0, 0x70, v0
	s_add_u32 s52, s14, 0x9140800
	s_addc_u32 s53, s15, 0
	v_mov_b32_e32 v14, v1
	v_mov_b32_e32 v15, v1
	v_mov_b32_e32 v4, v1
	v_mov_b32_e32 v5, v1
	v_mov_b32_e32 v6, v1
	v_mov_b32_e32 v7, v1
	v_mov_b32_e32 v8, v1
	v_mov_b32_e32 v9, v1
	v_mov_b32_e32 v10, v1
	v_mov_b32_e32 v11, v1
	s_waitcnt vmcnt(5)
	ds_write_b128 v3, v[18:21]
	v_lshl_add_u32 v3, v174, 1, v175
	s_waitcnt vmcnt(4)
	ds_write_b128 v3, v[22:25]
	v_lshl_add_u32 v3, v182, 1, v146
	v_mov_b32_e32 v12, v1
	v_mov_b32_e32 v13, v1
	v_lshlrev_b32_e32 v188, 1, v16
	s_mov_b32 s2, 0
	v_mul_u32_u24_e32 v143, 0x48, v170
	v_mul_u32_u24_e32 v139, 0x90, v170
	v_mov_b32_e32 v186, 0xf149f2ca
	s_waitcnt vmcnt(3)
	v_add_u32_e32 v254, v252, v3
	ds_write2_b64 v254, v[26:27], v[28:29] offset1:2
	v_lshl_add_u32 v3, v183, 1, v146
	s_waitcnt vmcnt(2)
	v_add_u32_e32 v255, v252, v3
	ds_write2_b64 v255, v[30:31], v[32:33] offset1:2
	v_lshl_add_u32 v3, v184, 1, v146
	s_waitcnt vmcnt(1)
	v_add_u32_e32 v254, v252, v3
	ds_write2_b64 v254, v[34:35], v[36:37] offset1:2
	v_lshl_add_u32 v3, v185, 1, v146
	s_waitcnt vmcnt(0)
	v_add_u32_e32 v255, v252, v3
	ds_write2_b64 v255, v[38:39], v[40:41] offset1:2
	v_lshl_add_u64 v[2:3], s[36:37], 0, v[72:73]
	v_or_b32_e32 v2, v2, v0
	v_lshl_add_u64 v[148:149], v[2:3], 0, s[16:17]
	v_lshl_add_u64 v[2:3], s[36:37], 0, v[68:69]
	v_or_b32_e32 v2, v2, v0
	v_lshl_add_u64 v[150:151], v[2:3], 0, s[16:17]
	v_lshl_add_u64 v[2:3], s[36:37], 0, v[64:65]
	v_or_b32_e32 v2, v2, v0
	v_lshl_add_u64 v[152:153], v[2:3], 0, s[16:17]
	v_lshl_add_u64 v[2:3], s[36:37], 0, v[60:61]
	v_or_b32_e32 v2, v2, v0
	v_lshl_add_u64 v[154:155], v[2:3], 0, s[16:17]
	v_lshl_add_u64 v[2:3], s[52:53], 0, v[54:55]
	v_or_b32_e32 v2, s88, v2
	v_lshl_add_u64 v[156:157], v[2:3], 0, v[56:57]
	v_lshl_add_u64 v[2:3], s[52:53], 0, v[46:47]
	v_or_b32_e32 v2, s88, v2
	v_lshl_add_u64 v[158:159], v[2:3], 0, v[48:49]
	v_mov_b32_e32 v0, v1
	v_mov_b32_e32 v2, v1
	v_mov_b32_e32 v3, v1
	v_mov_b64_e32 v[30:31], v[14:15]
	v_mov_b64_e32 v[46:47], v[14:15]
	v_mov_b64_e32 v[62:63], v[14:15]
	v_mov_b64_e32 v[78:79], v[14:15]
	v_mov_b32_e32 v190, 0
	v_mov_b64_e32 v[28:29], v[12:13]
	v_mov_b64_e32 v[26:27], v[10:11]
	v_mov_b64_e32 v[24:25], v[8:9]
	v_mov_b64_e32 v[22:23], v[6:7]
	v_mov_b64_e32 v[20:21], v[4:5]
	v_mov_b64_e32 v[18:19], v[2:3]
	v_mov_b64_e32 v[16:17], v[0:1]
	v_mov_b64_e32 v[44:45], v[12:13]
	v_mov_b64_e32 v[42:43], v[10:11]
	v_mov_b64_e32 v[40:41], v[8:9]
	v_mov_b64_e32 v[38:39], v[6:7]
	v_mov_b64_e32 v[36:37], v[4:5]
	v_mov_b64_e32 v[34:35], v[2:3]
	v_mov_b64_e32 v[32:33], v[0:1]
	v_mov_b64_e32 v[60:61], v[12:13]
	v_mov_b64_e32 v[58:59], v[10:11]
	v_mov_b64_e32 v[56:57], v[8:9]
	v_mov_b64_e32 v[54:55], v[6:7]
	v_mov_b64_e32 v[52:53], v[4:5]
	v_mov_b64_e32 v[50:51], v[2:3]
	v_mov_b64_e32 v[48:49], v[0:1]
	v_mov_b64_e32 v[76:77], v[12:13]
	v_mov_b64_e32 v[74:75], v[10:11]
	v_mov_b64_e32 v[72:73], v[8:9]
	v_mov_b64_e32 v[70:71], v[6:7]
	v_mov_b64_e32 v[68:69], v[4:5]
	v_mov_b64_e32 v[66:67], v[2:3]
	v_mov_b64_e32 v[64:65], v[0:1]
	s_mov_b32 s33, 0
	s_waitcnt lgkmcnt(0)
	s_barrier

; __device__ __forceinline__ f16v mfma16(h8 a, h8 b, f16v c) { return __builtin_amdgcn_mfma_f32_32x32x16_f16(a, b, c, 0, 0, 0); }
; template <int EQK, int EV, bool PF, class KP, class SC>
; __device__ __forceinline__ void flash_core(f16v (&o)[EV / 32], float& m_run, float& l_run, const h8 (&qf)[EQK / 16],
;                                            int kt0, int kt1, const KP& kp, const SC& sc, char* smem) {
;     ...
;   auto lstore = [&](int buf) {
;     h16* sK = base + buf * BUFH; h16* sV = sK + 64 * KLD;
; #pragma unroll
;     for (int i = 0; i < NKC; ++i) { int c = tid + 256 * i, row = c / KCH, kc = (c - row * KCH) * 8; *(h8*)(sK + row * KLD + kc) = rk[i]; }
; #pragma unroll
;     for (int i = 0; i < NVC; ++i) { int c = tid + 256 * i, e = c >> 3, kc = (c & 7) * 8; *(h8*)(sV + e * VLD + kc) = rv[i]; }
;   };
;     ...
;       h8 pf[4];
; #pragma unroll
;       for (int i = 0; i < 8; ++i) { pf[0][i] = (h16)p0[i]; pf[1][i] = (h16)p0[8 + i]; pf[2][i] = (h16)p1[i]; pf[3][i] = (h16)p1[8 + i]; }
; #pragma unroll
;       for (int et = 0; et < EV / 32; ++et) {
;         const h16* vb = sV + (et * 32 + l31) * VLD + hi * 4;
; #pragma unroll
;         for (int ks = 0; ks < 4; ++ks) {
;           h4 lo = *(const h4*)(vb + ks * 16), hh = *(const h4*)(vb + ks * 16 + 8);
;           h8 vf = {lo[0], lo[1], lo[2], lo[3], hh[0], hh[1], hh[2], hh[3]};
;           o[et] = mfma16(vf, pf[ks], o[et]);
;         }
;       }
;     }
;     if (PF) {
;       if (more) lstore(cur ^ 1);
;       __syncthreads();
.LBB0_1098:
	v_lshl_add_u32 v93, v147, 1, s41
	v_add_u32_e32 v93, v253, v93
	v_cvt_pk_f16_f32 v195, v194, v108
	v_cvt_pk_f16_f32 v194, v193, v102
	v_cvt_pk_f16_f32 v193, v192, v96
	v_cvt_pk_f16_f32 v192, v191, v0
	v_add_u32_e32 v0, v93, v139
	v_cvt_pk_f16_f32 v103, v103, v100
	v_cvt_pk_f16_f32 v100, v95, v14
	v_add_u32_e32 v14, 0x3000, v0
	v_cvt_pk_f16_f32 v167, v111, v166
	v_cvt_pk_f16_f32 v166, v161, v164
	v_cvt_pk_f16_f32 v164, v101, v106
	v_cvt_pk_f16_f32 v106, v105, v110
	v_cvt_pk_f16_f32 v105, v99, v104
	v_cvt_pk_f16_f32 v104, v97, v98
	ds_read_b128 v[96:99], v14 offset:1536
	s_waitcnt lgkmcnt(0)
	v_mfma_f32_32x32x16_f16 v[48:63], v[96:99], v[192:195], v[48:63]
	ds_read_b128 v[96:99], v14 offset:1568
	v_cvt_pk_f16_f32 v165, v107, v160
	v_cvt_pk_f16_f32 v102, v89, v90
	v_cvt_pk_f16_f32 v101, v15, v88
	v_lshl_add_u32 v163, v143, 1, v93
	v_add_u32_e32 v163, 0x2000, v163
	v_cvt_pk_f16_f32 v107, v109, v162
	s_waitcnt lgkmcnt(0)
	v_mfma_f32_32x32x16_f16 v[48:63], v[96:99], v[164:167], v[48:63]
	ds_read_b128 v[96:99], v14 offset:1600
	v_add_u32_e32 v15, 0x4800, v0
	ds_read_b128 v[196:199], v163 offset:1024
	v_add_u32_e32 v0, 0x5800, v0
	s_xor_b32 s33, s33, 1
	s_mul_i32 s41, s33, 0x6c00
	s_mov_b64 s[8:9], 0x80
	s_waitcnt lgkmcnt(1)
	v_mfma_f32_32x32x16_f16 v[48:63], v[96:99], v[100:103], v[48:63]
	ds_read_b128 v[96:99], v14 offset:1632
	v_add_f32_e32 v14, v92, v91
	v_fmac_f32_e32 v14, v190, v94
	ds_read_b128 v[88:91], v15 offset:96
	s_sub_i32 s2, s2, 64
	v_lshl_add_u64 v[148:149], v[148:149], 0, s[8:9]
	v_lshl_add_u64 v[150:151], v[150:151], 0, s[8:9]
	s_waitcnt lgkmcnt(1)
	v_mfma_f32_32x32x16_f16 v[48:63], v[96:99], v[104:107], v[48:63]
	ds_read_b128 v[96:99], v15
	v_lshl_add_u64 v[152:153], v[152:153], 0, s[8:9]
	v_lshl_add_u64 v[154:155], v[154:155], 0, s[8:9]
	s_mov_b64 s[8:9], 0x40000
	v_lshl_add_u64 v[156:157], v[156:157], 0, s[8:9]
	v_lshl_add_u64 v[158:159], v[158:159], 0, s[8:9]
	s_cmpk_lg_i32 s2, 0xf040
	v_mfma_f32_32x32x16_f16 v[64:79], v[196:199], v[192:195], v[64:79]
	ds_read_b128 v[196:199], v163 offset:1056
	s_waitcnt lgkmcnt(1)
	v_mfma_f32_32x32x16_f16 v[32:47], v[96:99], v[192:195], v[32:47]
	ds_read_b128 v[96:99], v15 offset:32
	s_waitcnt lgkmcnt(1)
	v_mfma_f32_32x32x16_f16 v[64:79], v[196:199], v[164:167], v[64:79]
	ds_read_b128 v[196:199], v163 offset:1088
	s_waitcnt lgkmcnt(1)
	v_mfma_f32_32x32x16_f16 v[32:47], v[96:99], v[164:167], v[32:47]
	ds_read_b128 v[96:99], v15 offset:64
	s_waitcnt lgkmcnt(1)
	v_mfma_f32_32x32x16_f16 v[64:79], v[196:199], v[100:103], v[64:79]
	ds_read_b128 v[196:199], v163 offset:1120
	s_waitcnt lgkmcnt(1)
	v_mfma_f32_32x32x16_f16 v[32:47], v[96:99], v[100:103], v[32:47]
	ds_read_b128 v[92:95], v0 offset:512
	ds_read_b128 v[96:99], v0 offset:544
	ds_read_b128 v[108:111], v0 offset:576
	ds_read_b128 v[160:163], v0 offset:608
	v_lshlrev_b32_e32 v0, 1, v172
	v_add3_u32 v0, s41, v0, v173
	s_waitcnt vmcnt(5)
	ds_write_b128 v0, v[6:9]
	v_lshlrev_b32_e32 v0, 1, v174
	v_add3_u32 v0, s41, v0, v175
	s_waitcnt vmcnt(4)
	ds_write_b128 v0, v[2:5]
	s_waitcnt lgkmcnt(5)
	v_mfma_f32_32x32x16_f16 v[16:31], v[92:95], v[192:195], v[16:31]
	v_lshlrev_b32_e32 v0, 1, v182
	v_add3_u32 v0, s41, v0, v146
	s_waitcnt vmcnt(3)
	v_add_u32_e32 v254, v252, v0
	ds_write2_b64 v254, v[128:129], v[130:131] offset1:2
	v_lshlrev_b32_e32 v0, 1, v183
	v_add3_u32 v0, s41, v0, v146
	s_waitcnt vmcnt(2)
	v_add_u32_e32 v255, v252, v0
	ds_write2_b64 v255, v[10:11], v[12:13] offset1:2
	v_lshlrev_b32_e32 v0, 1, v184
	s_waitcnt lgkmcnt(6)
	v_mfma_f32_32x32x16_f16 v[16:31], v[96:99], v[164:167], v[16:31]
	v_add3_u32 v0, s41, v0, v146
	s_waitcnt vmcnt(1)
	v_add_u32_e32 v254, v252, v0
	ds_write2_b64 v254, v[84:85], v[86:87] offset1:2
	v_lshlrev_b32_e32 v0, 1, v185
	v_add3_u32 v0, s41, v0, v146
	s_waitcnt vmcnt(0)
	v_add_u32_e32 v255, v252, v0
	ds_write2_b64 v255, v[80:81], v[82:83] offset1:2
	s_waitcnt lgkmcnt(0)
	s_barrier
	v_mfma_f32_32x32x16_f16 v[16:31], v[108:111], v[100:103], v[16:31]
	v_mfma_f32_32x32x16_f16 v[64:79], v[196:199], v[104:107], v[64:79]
	v_mfma_f32_32x32x16_f16 v[32:47], v[88:91], v[104:107], v[32:47]
	v_mfma_f32_32x32x16_f16 v[16:31], v[160:163], v[104:107], v[16:31]
	s_cbranch_scc0 .LBB0_1100
	v_mov_b32_e32 v190, v14
	s_branch .LBB0_1096

; __device__ __forceinline__ f16v mfma16(h8 a, h8 b, f16v c) { return __builtin_amdgcn_mfma_f32_32x32x16_f16(a, b, c, 0, 0, 0); }
; template <int EQK, int EV, bool PF, class KP, class SC>
; __device__ __forceinline__ void flash_core(f16v (&o)[EV / 32], float& m_run, float& l_run, const h8 (&qf)[EQK / 16],
;                                            int kt0, int kt1, const KP& kp, const SC& sc, char* smem) {
;     ...
;       h8 pf[4];
; #pragma unroll
;       for (int i = 0; i < 8; ++i) { pf[0][i] = (h16)p0[i]; pf[1][i] = (h16)p0[8 + i]; pf[2][i] = (h16)p1[i]; pf[3][i] = (h16)p1[8 + i]; }
; #pragma unroll
;       for (int et = 0; et < EV / 32; ++et) {
;         const h16* vb = sV + (et * 32 + l31) * VLD + hi * 4;
; #pragma unroll
;         for (int ks = 0; ks < 4; ++ks) {
;           h4 lo = *(const h4*)(vb + ks * 16), hh = *(const h4*)(vb + ks * 16 + 8);
;           h8 vf = {lo[0], lo[1], lo[2], lo[3], hh[0], hh[1], hh[2], hh[3]};
;           o[et] = mfma16(vf, pf[ks], o[et]);
;         }
;       }
; __device__ __forceinline__ void diff_attn_phase(const P& p_, int j, float lam_init, char* smem, bool dry = false) {
;     ...
;       const float inv = 1.f / l_run;
;       if (c == 0) {
; #pragma unroll
;         for (int et = 0; et < 4; ++et)
; #pragma unroll
;           for (int rg = 0; rg < 2; ++rg) {
;             h8 sv;
; #pragma unroll
;             for (int i = 0; i < 8; ++i) sv[i] = (h16)(o[et][rg * 8 + i] * inv);
;             *(h8*)(stash + et * 16 + rg * 8) = sv;
;           }
.LBB0_1102:
	v_lshl_add_u32 v110, v147, 1, s41
	v_add_u32_e32 v110, v253, v110
	v_lshl_add_u32 v101, v143, 1, v110
	v_add_u32_e32 v111, 0x2000, v101
	ds_read_b128 v[102:105], v111 offset:1024
	v_cvt_pk_f16_f32 v109, v85, v87
	v_cvt_pk_f16_f32 v108, v81, v82
	v_cvt_pk_f16_f32 v107, v10, v11
	v_cvt_pk_f16_f32 v106, v6, v7
	v_cvt_pk_f16_f32 v101, v99, v100
	v_cvt_pk_f16_f32 v100, v97, v98
	v_cvt_pk_f16_f32 v99, v93, v94
	v_cvt_pk_f16_f32 v98, v86, v88
	s_waitcnt lgkmcnt(0)
	v_mfma_f32_32x32x16_f16 v[64:79], v[102:105], v[106:109], v[64:79]
	ds_read_b128 v[102:105], v111 offset:1056
	v_cvt_pk_f16_f32 v87, v95, v96
	v_add_u32_e32 v96, v110, v139
	v_cvt_pk_f16_f32 v7, v12, v15
	v_cvt_pk_f16_f32 v6, v8, v9
	v_cvt_pk_f16_f32 v5, v4, v5
	v_cvt_pk_f16_f32 v4, v2, v3
	ds_read_b128 v[8:11], v111 offset:1120
	s_waitcnt lgkmcnt(1)
	v_mfma_f32_32x32x16_f16 v[64:79], v[102:105], v[98:101], v[64:79]
	ds_read_b128 v[102:105], v111 offset:1088
	v_add_u32_e32 v88, 0x3000, v96
	v_cvt_pk_f16_f32 v85, v83, v84
	v_cvt_pk_f16_f32 v84, v13, v80
	ds_read_b128 v[80:83], v88 offset:1536
	v_cvt_pk_f16_f32 v86, v89, v90
	s_ashr_i32 s41, s40, 31
	s_waitcnt lgkmcnt(1)
	v_mfma_f32_32x32x16_f16 v[64:79], v[102:105], v[4:7], v[64:79]
	s_lshl_b64 s[40:41], s[40:41], 15
	v_ashrrev_i32_e32 v143, 31, v142
	s_add_u32 s40, s5, s40
	v_lshlrev_b64 v[2:3], 7, v[142:143]
	s_addc_u32 s41, s26, s41
	v_lshl_add_u64 v[142:143], s[40:41], 0, v[2:3]
	v_add_f32_e32 v2, v91, v92
	v_mfma_f32_32x32x16_f16 v[64:79], v[8:11], v[84:87], v[64:79]
	ds_read_b128 v[8:11], v88 offset:1568
	v_fmac_f32_e32 v2, v14, v0
	v_add_u32_e32 v0, 0x4800, v96
	s_movk_i32 s2, 0x3000
	v_mov_b32_e32 v184, 0xf149f2ca
	v_mov_b32_e32 v189, 0
	s_waitcnt lgkmcnt(1)
	v_mfma_f32_32x32x16_f16 v[48:63], v[80:83], v[106:109], v[48:63]
	ds_read_b128 v[12:15], v88 offset:1600
	ds_read_b128 v[80:83], v88 offset:1632
	ds_read_b128 v[88:91], v0
	ds_read_b128 v[92:95], v0 offset:32
	s_waitcnt lgkmcnt(4)
	v_mfma_f32_32x32x16_f16 v[48:63], v[8:11], v[98:101], v[48:63]
	ds_read_b128 v[8:11], v0 offset:64
	ds_read_b128 v[102:105], v0 offset:96
	v_add_u32_e32 v0, 0x5800, v96
	ds_read_b128 v[110:113], v0 offset:512
	ds_read_b128 v[114:117], v0 offset:544
	ds_read_b128 v[118:121], v0 offset:576
	ds_read_b128 v[122:125], v0 offset:608
	v_div_scale_f32 v0, s[40:41], v2, v2, 1.0
	v_rcp_f32_e32 v3, v0
	s_waitcnt lgkmcnt(0)
	v_mfma_f32_32x32x16_f16 v[48:63], v[12:15], v[4:7], v[48:63]
	s_barrier
	v_fma_f32 v12, -v0, v3, 1.0
	v_fmac_f32_e32 v3, v12, v3
	v_div_scale_f32 v12, vcc, 1.0, v2, 1.0
	v_mul_f32_e32 v13, v12, v3
	v_fma_f32 v14, -v0, v13, v12
	v_mfma_f32_32x32x16_f16 v[32:47], v[88:91], v[106:109], v[32:47]
	v_fmac_f32_e32 v13, v14, v3
	v_fma_f32 v0, -v0, v13, v12
	v_div_fmas_f32 v0, v0, v3, v13
	v_div_fixup_f32 v0, v0, v2, 1.0
	v_mov_b32_e32 v2, v65
	v_mov_b32_e32 v3, v66
	v_pk_mul_f32 v[2:3], v[0:1], v[2:3] op_sel_hi:[0,1]
	v_mfma_f32_32x32x16_f16 v[16:31], v[110:113], v[106:109], v[16:31]
	v_cvt_pk_f16_f32 v13, v2, v3
	v_mov_b32_e32 v2, v67
	v_mov_b32_e32 v3, v68
	v_mul_f32_e64 v2, v0, v2
	v_mul_f32_e64 v3, v0, v3
	v_cvt_pk_f16_f32 v14, v2, v3
	v_mov_b32_e32 v2, v69
	v_mov_b32_e32 v3, v70
	v_mfma_f32_32x32x16_f16 v[32:47], v[92:95], v[98:101], v[32:47]
	v_mul_f32_e64 v2, v0, v2
	v_mul_f32_e64 v3, v0, v3
	v_fma_mixlo_f16 v12, v0, v64, 0
	v_cvt_pk_f16_f32 v2, v2, v3
	v_pack_b32_f16 v12, v12, v13
	v_alignbit_b32 v13, v14, v13, 16
	v_alignbit_b32 v14, v2, v14, 16
	v_lshrrev_b32_e32 v15, 16, v2
	v_mfma_f32_32x32x16_f16 v[48:63], v[80:83], v[84:87], v[48:63]
	v_mov_b32_e32 v2, v73
	v_mov_b32_e32 v3, v74
	v_mul_f32_e64 v2, v0, v2
	v_mul_f32_e64 v3, v0, v3
	v_fma_mixhi_f16 v15, v0, v71, 0
	global_store_dwordx4 v[142:143], v[12:15], off
	s_mov_b64 s[40:41], 0x80
	v_mfma_f32_32x32x16_f16 v[16:31], v[114:117], v[98:101], v[16:31]
	v_mfma_f32_32x32x16_f16 v[32:47], v[8:11], v[4:7], v[32:47]
	v_cvt_pk_f16_f32 v9, v2, v3
	v_mov_b32_e32 v2, v75
	v_mov_b32_e32 v3, v76
	v_mul_f32_e64 v2, v0, v2
	v_mul_f32_e64 v3, v0, v3
	v_cvt_pk_f16_f32 v10, v2, v3
	v_mov_b32_e32 v2, v77
	v_mov_b32_e32 v3, v78
	v_mfma_f32_32x32x16_f16 v[16:31], v[118:121], v[4:7], v[16:31]
	v_mov_b32_e32 v4, v51
	v_mov_b32_e32 v5, v52
	v_mul_f32_e64 v2, v0, v2
	v_mul_f32_e64 v3, v0, v3
	v_mul_f32_e64 v4, v0, v4
	v_mul_f32_e64 v5, v0, v5
	v_fma_mixlo_f16 v8, v0, v72, 0
	v_cvt_pk_f16_f32 v2, v2, v3
	v_cvt_pk_f16_f32 v6, v4, v5
	v_mov_b32_e32 v4, v53
	v_mov_b32_e32 v5, v54
	v_pack_b32_f16 v8, v8, v9
	v_alignbit_b32 v9, v10, v9, 16
	v_alignbit_b32 v10, v2, v10, 16
	v_lshrrev_b32_e32 v11, 16, v2
	v_mov_b32_e32 v2, v49
	v_mov_b32_e32 v3, v50
	v_pk_mul_f32 v[4:5], v[0:1], v[4:5] op_sel_hi:[0,1]
	v_fma_mixhi_f16 v11, v0, v79, 0
	v_pk_mul_f32 v[2:3], v[0:1], v[2:3] op_sel_hi:[0,1]
	v_cvt_pk_f16_f32 v5, v4, v5
	global_store_dwordx4 v[142:143], v[8:11], off offset:16
	v_cvt_pk_f16_f32 v3, v2, v3
	v_alignbit_b32 v4, v5, v6, 16
	v_fma_mixlo_f16 v8, v0, v48, 0
	v_lshrrev_b32_e32 v5, 16, v5
	v_pack_b32_f16 v2, v8, v3
	v_alignbit_b32 v3, v6, v3, 16
	v_fma_mixhi_f16 v5, v0, v55, 0
	global_store_dwordx4 v[142:143], v[2:5], off offset:32
	v_mfma_f32_32x32x16_f16 v[32:47], v[102:105], v[84:87], v[32:47]
	s_nop 0
	v_mov_b32_e32 v2, v57
	v_mov_b32_e32 v3, v58
	v_mul_f32_e64 v2, v0, v2
	v_mul_f32_e64 v3, v0, v3
	v_fma_mixlo_f16 v4, v0, v56, 0
	v_cvt_pk_f16_f32 v3, v2, v3
	v_pack_b32_f16 v2, v4, v3
	v_mov_b32_e32 v4, v59
	v_mov_b32_e32 v5, v60
	v_pk_mul_f32 v[4:5], v[0:1], v[4:5] op_sel_hi:[0,1]
	v_cvt_pk_f16_f32 v6, v4, v5
	v_mov_b32_e32 v4, v61
	v_mov_b32_e32 v5, v62
	v_pk_mul_f32 v[4:5], v[0:1], v[4:5] op_sel_hi:[0,1]
	v_cvt_pk_f16_f32 v5, v4, v5
	v_alignbit_b32 v4, v5, v6, 16
	v_lshrrev_b32_e32 v5, 16, v5
; __device__ __forceinline__ void diff_attn_phase(const P& p_, int j, float lam_init, char* smem, bool dry = false) {
;     ...
;       h8 qf[4];
; #pragma unroll
;       for (int d = 0; d < 4; ++d) qf[d] = *(const h8*)(QK + (size_t)tok * 2048 + h * 128 + c * 64 + d * 16 + hi * 8) * (h16)0.125f;
;     ...
;       if (c == 0) {
; #pragma unroll
;         for (int et = 0; et < 4; ++et)
; #pragma unroll
;           for (int rg = 0; rg < 2; ++rg) {
;             h8 sv;
; #pragma unroll
;             for (int i = 0; i < 8; ++i) sv[i] = (h16)(o[et][rg * 8 + i] * inv);
;             *(h8*)(stash + et * 16 + rg * 8) = sv;
;           }
	v_alignbit_b32 v3, v6, v3, 16
	v_fma_mixhi_f16 v5, v0, v63, 0
	global_store_dwordx4 v[142:143], v[2:5], off offset:48
	v_mfma_f32_32x32x16_f16 v[16:31], v[122:125], v[84:87], v[16:31]
	s_nop 0
	v_mov_b32_e32 v2, v33
	v_mov_b32_e32 v3, v34
	v_mul_f32_e64 v2, v0, v2
	v_mul_f32_e64 v3, v0, v3
	v_fma_mixlo_f16 v4, v0, v32, 0
	v_cvt_pk_f16_f32 v3, v2, v3
	v_pack_b32_f16 v2, v4, v3
	v_mov_b32_e32 v4, v35
	v_mov_b32_e32 v5, v36
	v_pk_mul_f32 v[4:5], v[0:1], v[4:5] op_sel_hi:[0,1]
	v_cvt_pk_f16_f32 v6, v4, v5
	v_mov_b32_e32 v4, v37
	v_mov_b32_e32 v5, v38
	v_pk_mul_f32 v[4:5], v[0:1], v[4:5] op_sel_hi:[0,1]
	v_cvt_pk_f16_f32 v5, v4, v5
	v_alignbit_b32 v4, v5, v6, 16
	v_lshrrev_b32_e32 v5, 16, v5
	v_alignbit_b32 v3, v6, v3, 16
	v_fma_mixhi_f16 v5, v0, v39, 0
	global_store_dwordx4 v[142:143], v[2:5], off offset:64
	s_nop 1
	v_mov_b32_e32 v2, v41
	v_mov_b32_e32 v3, v42
	v_pk_mul_f32 v[2:3], v[0:1], v[2:3] op_sel_hi:[0,1]
	v_fma_mixlo_f16 v4, v0, v40, 0
	v_cvt_pk_f16_f32 v3, v2, v3
	v_pack_b32_f16 v2, v4, v3
	v_mov_b32_e32 v4, v43
	v_mov_b32_e32 v5, v44
	v_pk_mul_f32 v[4:5], v[0:1], v[4:5] op_sel_hi:[0,1]
	v_cvt_pk_f16_f32 v6, v4, v5
	v_mov_b32_e32 v4, v45
	v_mov_b32_e32 v5, v46
	v_pk_mul_f32 v[4:5], v[0:1], v[4:5] op_sel_hi:[0,1]
	v_cvt_pk_f16_f32 v5, v4, v5
	v_alignbit_b32 v4, v5, v6, 16
	v_lshrrev_b32_e32 v5, 16, v5
	v_alignbit_b32 v3, v6, v3, 16
	v_fma_mixhi_f16 v5, v0, v47, 0
	global_store_dwordx4 v[142:143], v[2:5], off offset:80
	s_nop 1
	v_mov_b32_e32 v2, v17
	v_mov_b32_e32 v3, v18
	v_pk_mul_f32 v[2:3], v[0:1], v[2:3] op_sel_hi:[0,1]
	v_fma_mixlo_f16 v4, v0, v16, 0
	v_cvt_pk_f16_f32 v3, v2, v3
	v_pack_b32_f16 v2, v4, v3
	v_mov_b32_e32 v4, v19
	v_mov_b32_e32 v5, v20
	v_pk_mul_f32 v[4:5], v[0:1], v[4:5] op_sel_hi:[0,1]
	v_cvt_pk_f16_f32 v6, v4, v5
	v_mov_b32_e32 v4, v21
	v_mov_b32_e32 v5, v22
	v_pk_mul_f32 v[4:5], v[0:1], v[4:5] op_sel_hi:[0,1]
	v_cvt_pk_f16_f32 v5, v4, v5
	v_alignbit_b32 v4, v5, v6, 16
	v_lshrrev_b32_e32 v5, 16, v5
	v_alignbit_b32 v3, v6, v3, 16
	v_fma_mixhi_f16 v5, v0, v23, 0
	global_store_dwordx4 v[142:143], v[2:5], off offset:96
	s_nop 1
	v_mov_b32_e32 v2, v25
	v_mov_b32_e32 v3, v26
	v_pk_mul_f32 v[2:3], v[0:1], v[2:3] op_sel_hi:[0,1]
	v_fma_mixlo_f16 v4, v0, v24, 0
	v_cvt_pk_f16_f32 v3, v2, v3
	v_pack_b32_f16 v2, v4, v3
	v_mov_b32_e32 v4, v27
	v_mov_b32_e32 v5, v28
	v_pk_mul_f32 v[4:5], v[0:1], v[4:5] op_sel_hi:[0,1]
	v_cvt_pk_f16_f32 v6, v4, v5
	v_mov_b32_e32 v4, v29
	v_mov_b32_e32 v5, v30
	v_pk_mul_f32 v[4:5], v[0:1], v[4:5] op_sel_hi:[0,1]
	v_cvt_pk_f16_f32 v5, v4, v5
	v_alignbit_b32 v4, v5, v6, 16
	v_lshrrev_b32_e32 v5, 16, v5
	v_alignbit_b32 v3, v6, v3, 16
	v_fma_mixhi_f16 v5, v0, v31, 0
	global_store_dwordx4 v[142:143], v[2:5], off offset:112
	v_mov_b32_e32 v0, v180
	global_load_dwordx4 v[2:5], v[144:145], off offset:224
	global_load_dwordx4 v[6:9], v[144:145], off offset:192
	global_load_dwordx4 v[10:13], v[144:145], off offset:160
	global_load_dwordx4 v[14:17], v[144:145], off offset:128
	s_nop 0
	v_add_u32_e32 v28, 0x100, v0
	v_ashrrev_i32_e32 v18, 31, v0
	v_ashrrev_i32_e32 v20, 31, v28
	v_lshrrev_b32_e32 v18, 29, v18
	v_lshrrev_b32_e32 v20, 29, v20
	v_add_u32_e32 v18, v0, v18
	v_add_u32_e32 v20, v28, v20
	v_ashrrev_i32_e32 v42, 3, v18
	v_ashrrev_i32_e32 v50, 3, v20
	v_lshlrev_b32_e32 v18, 6, v42
	v_lshlrev_b32_e32 v26, 3, v0
	v_lshlrev_b32_e32 v20, 6, v50
	v_lshlrev_b32_e32 v21, 3, v28
	v_sub_u32_e32 v44, v26, v18
	v_ashrrev_i32_e32 v43, 31, v42
	v_sub_u32_e32 v52, v21, v20
	v_ashrrev_i32_e32 v51, 31, v50
	v_lshlrev_b64 v[46:47], 12, v[42:43]
	v_ashrrev_i32_e32 v45, 31, v44
	v_lshlrev_b64 v[54:55], 12, v[50:51]
	v_ashrrev_i32_e32 v53, 31, v52
	v_ashrrev_i32_e32 v58, 3, v0
	v_ashrrev_i32_e32 v62, 3, v28
	v_add_u32_e32 v34, 0x200, v0
	v_lshl_add_u64 v[18:19], s[34:35], 0, v[46:47]
	v_lshlrev_b64 v[48:49], 1, v[44:45]
	v_lshl_add_u64 v[20:21], s[34:35], 0, v[54:55]
	v_lshlrev_b64 v[56:57], 1, v[52:53]
	v_ashrrev_i32_e32 v59, 31, v58
	v_ashrrev_i32_e32 v63, 31, v62
	v_ashrrev_i32_e32 v66, 3, v34
	v_add_u32_e32 v38, 0x300, v0
	v_lshl_add_u64 v[18:19], v[18:19], 0, v[48:49]
	v_lshl_add_u64 v[22:23], v[20:21], 0, v[56:57]
	v_and_b32_e32 v29, 56, v26
	v_lshlrev_b64 v[60:61], 15, v[58:59]
	v_lshlrev_b64 v[64:65], 15, v[62:63]
	v_ashrrev_i32_e32 v67, 31, v66
	v_ashrrev_i32_e32 v70, 3, v38
	s_barrier
; template <int EQK, int EV, bool PF, class KP, class SC>
; __device__ __forceinline__ void flash_core(f16v (&o)[EV / 32], float& m_run, float& l_run, const h8 (&qf)[EQK / 16],
;                                            int kt0, int kt1, const KP& kp, const SC& sc, char* smem) {
;     ...
;   auto gload = [&](int kt) {
; #pragma unroll
;     for (int i = 0; i < NKC; ++i) { int c = tid + 256 * i, row = c / KCH, kc = (c - row * KCH) * 8; rk[i] = *(const h8*)(kp.kptr(kt, row) + kc); }
; #pragma unroll
;     for (int i = 0; i < NVC; ++i) { int c = tid + 256 * i, e = c >> 3, kc = (c & 7) * 8; rv[i] = *(const h8*)(kp.vptr(kt, e) + kc); }
;   };
;   auto lstore = [&](int buf) {
;     h16* sK = base + buf * BUFH; h16* sV = sK + 64 * KLD;
; #pragma unroll
;     for (int i = 0; i < NKC; ++i) { int c = tid + 256 * i, row = c / KCH, kc = (c - row * KCH) * 8; *(h8*)(sK + row * KLD + kc) = rk[i]; }
; #pragma unroll
;     for (int i = 0; i < NVC; ++i) { int c = tid + 256 * i, e = c >> 3, kc = (c & 7) * 8; *(h8*)(sV + e * VLD + kc) = rv[i]; }
;   };
;   __syncthreads();
;   gload(kt0); lstore(0);
;   __syncthreads();
; __device__ __forceinline__ void diff_attn_phase(const P& p_, int j, float lam_init, char* smem, bool dry = false) {
;     ...
;       h8 qf[4];
; #pragma unroll
;       for (int d = 0; d < 4; ++d) qf[d] = *(const h8*)(QK + (size_t)tok * 2048 + h * 128 + c * 64 + d * 16 + hi * 8) * (h16)0.125f;
; #pragma unroll
;       for (int et = 0; et < 4; ++et)
; #pragma unroll
;         for (int r = 0; r < 16; ++r) o[et][r] = 0.f;
;       float m_run = -1e30f, l_run = 0.f;
;       KPDiff kp{QK + (size_t)b * S_ * 2048 + 1024 + h * 128 + c * 64, VT + (size_t)(h * 128) * T_ + b * S_};
;       SCDiff sc{exp2f(-(float)(h + 1)), qt * 128};
;       flash_core<64, 128, true>(o, m_run, l_run, qf, 0, 64, kp, sc, smem);
	global_load_dwordx4 v[18:21], v[18:19], off offset:2176
	s_nop 0
	global_load_dwordx4 v[22:25], v[22:23], off offset:2176
	v_lshl_add_u64 v[26:27], s[24:25], 0, v[60:61]
	v_lshlrev_b32_e32 v144, 1, v29
	v_mov_b32_e32 v145, v1
	v_lshl_add_u64 v[28:29], s[24:25], 0, v[64:65]
	v_lshlrev_b64 v[68:69], 15, v[66:67]
	v_ashrrev_i32_e32 v71, 31, v70
	v_lshl_add_u64 v[26:27], v[26:27], 0, v[144:145]
	v_lshl_add_u64 v[30:31], v[28:29], 0, v[144:145]
	v_lshl_add_u64 v[34:35], s[24:25], 0, v[68:69]
	v_lshlrev_b64 v[72:73], 15, v[70:71]
	global_load_dwordx4 v[26:29], v[26:27], off
	s_nop 0
	global_load_dwordx4 v[30:33], v[30:31], off
	v_lshl_add_u64 v[34:35], v[34:35], 0, v[144:145]
	v_lshl_add_u64 v[38:39], s[24:25], 0, v[72:73]
	global_load_dwordx4 v[34:37], v[34:35], off
	v_lshl_add_u64 v[38:39], v[38:39], 0, v[144:145]
	global_load_dwordx4 v[38:41], v[38:39], off
	v_lshlrev_b32_e32 v172, 1, v44
	v_lshlrev_b32_e32 v174, 1, v52
	v_and_b32_e32 v167, 31, v0
	v_mul_u32_u24_e32 v145, 0x48, v167
	v_mul_u32_u24_e32 v139, 0x90, v167
	s_waitcnt vmcnt(9)
	v_pk_mul_f16 v115, v5, s2 op_sel_hi:[1,0]
	s_waitcnt vmcnt(8)
	v_pk_mul_f16 v119, v9, s2 op_sel_hi:[1,0]
	s_waitcnt vmcnt(7)
	v_pk_mul_f16 v123, v13, s2 op_sel_hi:[1,0]
	s_waitcnt vmcnt(6)
	v_pk_mul_f16 v127, v17, s2 op_sel_hi:[1,0]
	v_pk_mul_f16 v126, v16, s2 op_sel_hi:[1,0]
	v_pk_mul_f16 v125, v15, s2 op_sel_hi:[1,0]
	v_pk_mul_f16 v124, v14, s2 op_sel_hi:[1,0]
	v_pk_mul_f16 v122, v12, s2 op_sel_hi:[1,0]
	v_pk_mul_f16 v121, v11, s2 op_sel_hi:[1,0]
	v_pk_mul_f16 v120, v10, s2 op_sel_hi:[1,0]
	v_pk_mul_f16 v118, v8, s2 op_sel_hi:[1,0]
	v_pk_mul_f16 v117, v7, s2 op_sel_hi:[1,0]
	v_pk_mul_f16 v116, v6, s2 op_sel_hi:[1,0]
	v_pk_mul_f16 v114, v4, s2 op_sel_hi:[1,0]
	v_pk_mul_f16 v113, v3, s2 op_sel_hi:[1,0]
	v_pk_mul_f16 v112, v2, s2 op_sel_hi:[1,0]
	s_movk_i32 s2, 0x48
	v_ashrrev_i32_e32 v3, 1, v0
	v_mul_lo_u32 v171, v42, s2
	v_and_b32_e32 v170, 0xffffffe0, v3
	v_lshl_add_u32 v3, v171, 1, v172
	v_mul_lo_u32 v173, v50, s2
	v_mul_lo_u32 v175, v58, s2
	v_mul_lo_u32 v182, v62, s2
	v_mul_lo_u32 v183, v66, s2
	v_bfe_u32 v2, v0, 5, 1
	v_mul_lo_u32 v185, v70, s2
	v_lshlrev_b32_e32 v16, 3, v2
	v_lshlrev_b32_e32 v166, 2, v2
	v_add3_u32 v2, s48, v170, v167
	v_and_b32_e32 v0, 7, v0
	v_sub_u32_e32 v186, v2, v166
	v_lshlrev_b32_e32 v0, 4, v0
	s_add_u32 s2, s14, s88
	s_addc_u32 s15, s15, 0
	s_add_u32 s14, s2, 0x9140880
	s_addc_u32 s15, s15, 0
	v_mov_b32_e32 v14, v1
	v_mov_b32_e32 v15, v1
	v_mov_b32_e32 v4, v1
	v_mov_b32_e32 v5, v1
	v_mov_b32_e32 v6, v1
	v_mov_b32_e32 v7, v1
	v_mov_b32_e32 v8, v1
	v_mov_b32_e32 v9, v1
	v_mov_b32_e32 v10, v1
	s_waitcnt vmcnt(5)
	ds_write_b128 v3, v[18:21]
	v_lshl_add_u32 v3, v173, 1, v174
	s_waitcnt vmcnt(4)
	ds_write_b128 v3, v[22:25]
	v_lshl_add_u32 v3, v175, 1, v144
	v_mov_b32_e32 v11, v1
	v_mov_b32_e32 v12, v1
	v_mov_b32_e32 v13, v1
	v_lshlrev_b32_e32 v187, 1, v16
	s_mov_b32 s2, 0
	s_waitcnt vmcnt(3)
	v_add_u32_e32 v254, v252, v3
	ds_write2_b64 v254, v[26:27], v[28:29] offset1:2
	v_lshl_add_u32 v3, v182, 1, v144
	s_waitcnt vmcnt(2)
	v_add_u32_e32 v255, v252, v3
	ds_write2_b64 v255, v[30:31], v[32:33] offset1:2
	v_lshl_add_u32 v3, v183, 1, v144
	s_waitcnt vmcnt(1)
	v_add_u32_e32 v254, v252, v3
	ds_write2_b64 v254, v[34:35], v[36:37] offset1:2
	v_lshl_add_u32 v3, v185, 1, v144
	s_waitcnt vmcnt(0)
	v_add_u32_e32 v255, v252, v3
	ds_write2_b64 v255, v[38:39], v[40:41] offset1:2
	v_lshl_add_u64 v[2:3], s[36:37], 0, v[72:73]
	v_lshl_add_u64 v[2:3], v[2:3], 0, v[0:1]
	v_lshl_add_u64 v[146:147], v[2:3], 0, s[16:17]
	v_lshl_add_u64 v[2:3], s[36:37], 0, v[68:69]
	v_lshl_add_u64 v[2:3], v[2:3], 0, v[0:1]
	v_lshl_add_u64 v[148:149], v[2:3], 0, s[16:17]
	v_lshl_add_u64 v[2:3], s[36:37], 0, v[64:65]
	v_lshl_add_u64 v[2:3], v[2:3], 0, v[0:1]
	v_lshl_add_u64 v[150:151], v[2:3], 0, s[16:17]
	v_lshl_add_u64 v[2:3], s[36:37], 0, v[60:61]
	v_lshl_add_u64 v[2:3], v[2:3], 0, v[0:1]
	v_lshl_add_u64 v[152:153], v[2:3], 0, s[16:17]
	v_lshl_add_u64 v[2:3], s[14:15], 0, v[54:55]
	v_lshl_add_u64 v[154:155], v[2:3], 0, v[56:57]
	v_lshl_add_u64 v[2:3], s[14:15], 0, v[46:47]
	v_lshl_add_u64 v[156:157], v[2:3], 0, v[48:49]
	v_mov_b32_e32 v0, v1
	v_mov_b32_e32 v2, v1
	v_mov_b32_e32 v3, v1
	v_mov_b64_e32 v[30:31], v[14:15]
	v_mov_b64_e32 v[46:47], v[14:15]
	v_mov_b64_e32 v[62:63], v[14:15]
	v_mov_b64_e32 v[78:79], v[14:15]
	v_mov_b64_e32 v[28:29], v[12:13]
	v_mov_b64_e32 v[26:27], v[10:11]
	v_mov_b64_e32 v[24:25], v[8:9]
	v_mov_b64_e32 v[22:23], v[6:7]
	v_mov_b64_e32 v[20:21], v[4:5]
	v_mov_b64_e32 v[18:19], v[2:3]
	v_mov_b64_e32 v[16:17], v[0:1]
	v_mov_b64_e32 v[44:45], v[12:13]
	v_mov_b64_e32 v[42:43], v[10:11]
	v_mov_b64_e32 v[40:41], v[8:9]
	v_mov_b64_e32 v[38:39], v[6:7]
	v_mov_b64_e32 v[36:37], v[4:5]
	v_mov_b64_e32 v[34:35], v[2:3]
	v_mov_b64_e32 v[32:33], v[0:1]
	v_mov_b64_e32 v[60:61], v[12:13]
	v_mov_b64_e32 v[58:59], v[10:11]
	v_mov_b64_e32 v[56:57], v[8:9]
	v_mov_b64_e32 v[54:55], v[6:7]
	v_mov_b64_e32 v[52:53], v[4:5]
	v_mov_b64_e32 v[50:51], v[2:3]
	v_mov_b64_e32 v[48:49], v[0:1]
	v_mov_b64_e32 v[76:77], v[12:13]
	v_mov_b64_e32 v[74:75], v[10:11]
	v_mov_b64_e32 v[72:73], v[8:9]
	v_mov_b64_e32 v[70:71], v[6:7]
	v_mov_b64_e32 v[68:69], v[4:5]
	v_mov_b64_e32 v[66:67], v[2:3]
	v_mov_b64_e32 v[64:65], v[0:1]
	s_mov_b32 s14, 0
	s_waitcnt lgkmcnt(0)
	s_barrier

; __device__ __forceinline__ f16v mfma16(h8 a, h8 b, f16v c) { return __builtin_amdgcn_mfma_f32_32x32x16_f16(a, b, c, 0, 0, 0); }
; template <int EQK, int EV, bool PF, class KP, class SC>
; __device__ __forceinline__ void flash_core(f16v (&o)[EV / 32], float& m_run, float& l_run, const h8 (&qf)[EQK / 16],
;                                            int kt0, int kt1, const KP& kp, const SC& sc, char* smem) {
;     ...
;       h8 pf[4];
; #pragma unroll
;       for (int i = 0; i < 8; ++i) { pf[0][i] = (h16)p0[i]; pf[1][i] = (h16)p0[8 + i]; pf[2][i] = (h16)p1[i]; pf[3][i] = (h16)p1[8 + i]; }
; #pragma unroll
;       for (int et = 0; et < EV / 32; ++et) {
;         const h16* vb = sV + (et * 32 + l31) * VLD + hi * 4;
; #pragma unroll
;         for (int ks = 0; ks < 4; ++ks) {
;           h4 lo = *(const h4*)(vb + ks * 16), hh = *(const h4*)(vb + ks * 16 + 8);
;           h8 vf = {lo[0], lo[1], lo[2], lo[3], hh[0], hh[1], hh[2], hh[3]};
;           o[et] = mfma16(vf, pf[ks], o[et]);
;         }
;       }
;     }
;     if (PF) {
;       if (more) lstore(cur ^ 1);
;       __syncthreads();
;       cur ^= 1;
;     } else if (more) {
;       __syncthreads();
;       gload(kt + 1); lstore(0);
;       __syncthreads();
;     }
.LBB0_1105:
	v_lshl_add_u32 v93, v166, 1, s15
	v_add_u32_e32 v93, v253, v93
	v_cvt_pk_f16_f32 v190, v190, v0
	v_add_u32_e32 v0, v93, v139
	v_cvt_pk_f16_f32 v103, v103, v100
	v_cvt_pk_f16_f32 v100, v95, v14
	v_add_u32_e32 v14, 0x3000, v0
	v_cvt_pk_f16_f32 v191, v191, v96
	v_cvt_pk_f16_f32 v165, v111, v164
	v_cvt_pk_f16_f32 v164, v159, v162
	v_cvt_pk_f16_f32 v162, v101, v106
	v_cvt_pk_f16_f32 v106, v105, v110
	v_cvt_pk_f16_f32 v105, v99, v104
	v_cvt_pk_f16_f32 v104, v97, v98
	ds_read_b128 v[96:99], v14 offset:1536
	v_cvt_pk_f16_f32 v193, v193, v108
	v_cvt_pk_f16_f32 v192, v192, v102
	v_cvt_pk_f16_f32 v163, v107, v158
	v_cvt_pk_f16_f32 v102, v89, v90
	s_waitcnt lgkmcnt(0)
	v_mfma_f32_32x32x16_f16 v[48:63], v[96:99], v[190:193], v[48:63]
	ds_read_b128 v[96:99], v14 offset:1568
	v_cvt_pk_f16_f32 v101, v15, v88
	v_lshl_add_u32 v161, v145, 1, v93
	v_add_u32_e32 v161, 0x2000, v161
	v_cvt_pk_f16_f32 v107, v109, v160
	v_add_u32_e32 v15, 0x4800, v0
	ds_read_b128 v[194:197], v161 offset:1024
	s_waitcnt lgkmcnt(1)
	v_mfma_f32_32x32x16_f16 v[48:63], v[96:99], v[162:165], v[48:63]
	ds_read_b128 v[96:99], v14 offset:1600
	v_add_u32_e32 v0, 0x5800, v0
	s_xor_b32 s14, s14, 1
	s_mul_i32 s15, s14, 0x6c00
	s_sub_i32 s2, s2, 64
	s_mov_b64 s[8:9], 0x40000
	v_lshl_add_u64 v[146:147], v[146:147], 0, s[40:41]
	s_waitcnt lgkmcnt(0)
	v_mfma_f32_32x32x16_f16 v[48:63], v[96:99], v[100:103], v[48:63]
	ds_read_b128 v[96:99], v14 offset:1632
	v_add_f32_e32 v14, v92, v91
	v_fmac_f32_e32 v14, v189, v94
	ds_read_b128 v[88:91], v15 offset:96
	v_lshl_add_u64 v[148:149], v[148:149], 0, s[40:41]
	v_lshl_add_u64 v[150:151], v[150:151], 0, s[40:41]
	v_lshl_add_u64 v[152:153], v[152:153], 0, s[40:41]
	s_waitcnt lgkmcnt(1)
	v_mfma_f32_32x32x16_f16 v[48:63], v[96:99], v[104:107], v[48:63]
	ds_read_b128 v[96:99], v15
	v_lshl_add_u64 v[154:155], v[154:155], 0, s[8:9]
	v_lshl_add_u64 v[156:157], v[156:157], 0, s[8:9]
	s_cmpk_lg_i32 s2, 0xf040
	v_mfma_f32_32x32x16_f16 v[64:79], v[194:197], v[190:193], v[64:79]
	ds_read_b128 v[194:197], v161 offset:1056
	s_waitcnt lgkmcnt(1)
	v_mfma_f32_32x32x16_f16 v[32:47], v[96:99], v[190:193], v[32:47]
	ds_read_b128 v[96:99], v15 offset:32
	s_waitcnt lgkmcnt(1)
	v_mfma_f32_32x32x16_f16 v[64:79], v[194:197], v[162:165], v[64:79]
	ds_read_b128 v[194:197], v161 offset:1088
	s_waitcnt lgkmcnt(1)
	v_mfma_f32_32x32x16_f16 v[32:47], v[96:99], v[162:165], v[32:47]
	ds_read_b128 v[96:99], v15 offset:64
	s_waitcnt lgkmcnt(1)
	v_mfma_f32_32x32x16_f16 v[64:79], v[194:197], v[100:103], v[64:79]
	ds_read_b128 v[194:197], v161 offset:1120
	s_waitcnt lgkmcnt(1)
	v_mfma_f32_32x32x16_f16 v[32:47], v[96:99], v[100:103], v[32:47]
	ds_read_b128 v[92:95], v0 offset:512
	ds_read_b128 v[96:99], v0 offset:544
	ds_read_b128 v[108:111], v0 offset:576
	ds_read_b128 v[158:161], v0 offset:608
	v_lshlrev_b32_e32 v0, 1, v171
	v_add3_u32 v0, s15, v0, v172
	s_waitcnt vmcnt(5)
	ds_write_b128 v0, v[6:9]
	v_lshlrev_b32_e32 v0, 1, v173
	v_add3_u32 v0, s15, v0, v174
	s_waitcnt vmcnt(4)
	ds_write_b128 v0, v[2:5]
	s_waitcnt lgkmcnt(5)
	v_mfma_f32_32x32x16_f16 v[16:31], v[92:95], v[190:193], v[16:31]
	v_lshlrev_b32_e32 v0, 1, v175
	v_add3_u32 v0, s15, v0, v144
	s_waitcnt vmcnt(3)
	v_add_u32_e32 v254, v252, v0
	ds_write2_b64 v254, v[128:129], v[130:131] offset1:2
	v_lshlrev_b32_e32 v0, 1, v182
	v_add3_u32 v0, s15, v0, v144
	s_waitcnt vmcnt(2)
	v_add_u32_e32 v255, v252, v0
	ds_write2_b64 v255, v[10:11], v[12:13] offset1:2
	v_lshlrev_b32_e32 v0, 1, v183
	s_waitcnt lgkmcnt(6)
	v_mfma_f32_32x32x16_f16 v[16:31], v[96:99], v[162:165], v[16:31]
	v_add3_u32 v0, s15, v0, v144
	s_waitcnt vmcnt(1)
	v_add_u32_e32 v254, v252, v0
	ds_write2_b64 v254, v[84:85], v[86:87] offset1:2
	v_lshlrev_b32_e32 v0, 1, v185
	v_add3_u32 v0, s15, v0, v144
	s_waitcnt vmcnt(0)
	v_add_u32_e32 v255, v252, v0
	ds_write2_b64 v255, v[80:81], v[82:83] offset1:2
	s_waitcnt lgkmcnt(0)
	s_barrier
	v_mfma_f32_32x32x16_f16 v[16:31], v[108:111], v[100:103], v[16:31]
	v_mfma_f32_32x32x16_f16 v[64:79], v[194:197], v[104:107], v[64:79]
	v_mfma_f32_32x32x16_f16 v[32:47], v[88:91], v[104:107], v[32:47]
	v_mfma_f32_32x32x16_f16 v[16:31], v[158:161], v[104:107], v[16:31]
	s_cbranch_scc0 .LBB0_1107
	v_mov_b32_e32 v189, v14
	s_branch .LBB0_1103

; __global__ void __launch_bounds__(256, 2) fwd_megakernel(P p) {
;   cg::grid_group grid = cg::this_grid();
;   __shared__ __attribute__((aligned(16))) char smem[SMEM_BYTES];
	.amdhsa_kernel _Z14fwd_megakernel1P
		.amdhsa_group_segment_fixed_size 73748
		.amdhsa_private_segment_fixed_size 0
		.amdhsa_kernarg_size 544
		.amdhsa_user_sgpr_count 2
		.amdhsa_user_sgpr_dispatch_ptr 0
		.amdhsa_user_sgpr_queue_ptr 0
		.amdhsa_user_sgpr_kernarg_segment_ptr 1
		.amdhsa_user_sgpr_dispatch_id 0
		.amdhsa_user_sgpr_kernarg_preload_length 0
		.amdhsa_user_sgpr_kernarg_preload_offset 0
		.amdhsa_user_sgpr_private_segment_size 0
		.amdhsa_uses_dynamic_stack 0
		.amdhsa_enable_private_segment 0
		.amdhsa_system_sgpr_workgroup_id_x 1
		.amdhsa_system_sgpr_workgroup_id_y 0
		.amdhsa_system_sgpr_workgroup_id_z 0
		.amdhsa_system_sgpr_workgroup_info 0
		.amdhsa_system_vgpr_workitem_id 2
		.amdhsa_next_free_vgpr 256
		.amdhsa_next_free_sgpr 100
		.amdhsa_accum_offset 256
		.amdhsa_reserve_vcc 1
		.amdhsa_float_round_mode_32 0
		.amdhsa_float_round_mode_16_64 0
		.amdhsa_float_denorm_mode_32 3
		.amdhsa_float_denorm_mode_16_64 3
		.amdhsa_dx10_clamp 1
		.amdhsa_ieee_mode 1
		.amdhsa_fp16_overflow 0
		.amdhsa_tg_split 0
		.amdhsa_exception_fp_ieee_invalid_op 0
		.amdhsa_exception_fp_denorm_src 0
		.amdhsa_exception_fp_ieee_div_zero 0
		.amdhsa_exception_fp_ieee_overflow 0
		.amdhsa_exception_fp_ieee_underflow 0
		.amdhsa_exception_fp_ieee_inexact 0
		.amdhsa_exception_int_div_zero 0
	.end_amdhsa_kernel

; __global__ void __launch_bounds__(256, 2) fwd_megakernel(P p) {
;   cg::grid_group grid = cg::this_grid();
;   __shared__ __attribute__((aligned(16))) char smem[SMEM_BYTES];
amdhsa.kernels:
  - .agpr_count:     0
    .args:
      - .offset:         0
        .size:           288
        .value_kind:     by_value
      - .offset:         288
        .size:           4
        .value_kind:     hidden_block_count_x
      - .offset:         292
        .size:           4
        .value_kind:     hidden_block_count_y
      - .offset:         296
        .size:           4
        .value_kind:     hidden_block_count_z
      - .offset:         300
        .size:           2
        .value_kind:     hidden_group_size_x
      - .offset:         302
        .size:           2
        .value_kind:     hidden_group_size_y
      - .offset:         304
        .size:           2
        .value_kind:     hidden_group_size_z
      - .offset:         306
        .size:           2
        .value_kind:     hidden_remainder_x
      - .offset:         308
        .size:           2
        .value_kind:     hidden_remainder_y
      - .offset:         310
        .size:           2
        .value_kind:     hidden_remainder_z
      - .offset:         328
        .size:           8
        .value_kind:     hidden_global_offset_x
      - .offset:         336
        .size:           8
        .value_kind:     hidden_global_offset_y
      - .offset:         344
        .size:           8
        .value_kind:     hidden_global_offset_z
      - .offset:         352
        .size:           2
        .value_kind:     hidden_grid_dims
      - .offset:         376
        .size:           8
        .value_kind:     hidden_multigrid_sync_arg
    .group_segment_fixed_size: 73748
    .kernarg_segment_align: 8
    .kernarg_segment_size: 544
    .language:       OpenCL C
    .language_version:
      - 2
      - 0
    .max_flat_workgroup_size: 256
    .name:           _Z14fwd_megakernel1P
    .private_segment_fixed_size: 0
    .sgpr_count:     106
    .sgpr_spill_count: 149
    .symbol:         _Z14fwd_megakernel1P.kd
    .uniform_work_group_size: 1
    .uses_dynamic_stack: false
    .vgpr_count:     256
    .vgpr_spill_count: 0
    .wavefront_size: 64
